# v15 with the count passes redone: per-lane VALU counting (v_cmp into 3 rotating masks + v_addc) and one DPP reduction per pass instead of s_bcnt1+s_add per element
# speedup vs baseline: 1.0132x; 1.0084x over previous
.LBB0_1099:
	s_waitcnt vmcnt(0) lgkmcnt(0)
	s_cmpk_lt_u32 s3, 0x400
	s_cbranch_scc1 .LBB0_1106
	v_lshl_or_b32 v3, v6, 23, v172
	s_waitcnt vmcnt(0) lgkmcnt(0)
	v_mov_b32_e32 v204, 0
	v_cmp_ge_u32_e32 vcc, v19, v3
	v_cmp_ge_u32_e64 s[98:99], v13, v3
	v_cmp_ge_u32_e64 s[100:101], v20, v3
	v_addc_co_u32_e32 v204, vcc, 0, v204, vcc
	v_cmp_ge_u32_e32 vcc, v12, v3
	v_addc_co_u32_e64 v204, s[98:99], 0, v204, s[98:99]
	v_cmp_ge_u32_e64 s[98:99], v18, v3
	v_addc_co_u32_e64 v204, s[100:101], 0, v204, s[100:101]
	v_cmp_ge_u32_e64 s[100:101], v10, v3
	v_addc_co_u32_e32 v204, vcc, 0, v204, vcc
	v_cmp_ge_u32_e32 vcc, v17, v3
	v_addc_co_u32_e64 v204, s[98:99], 0, v204, s[98:99]
	v_cmp_ge_u32_e64 s[98:99], v9, v3
	v_addc_co_u32_e64 v204, s[100:101], 0, v204, s[100:101]
	v_cmp_ge_u32_e64 s[100:101], v16, v3
	v_addc_co_u32_e32 v204, vcc, 0, v204, vcc
	v_cmp_ge_u32_e32 vcc, v8, v3
	v_addc_co_u32_e64 v204, s[98:99], 0, v204, s[98:99]
	v_cmp_ge_u32_e64 s[98:99], v15, v3
	v_addc_co_u32_e64 v204, s[100:101], 0, v204, s[100:101]
	v_cmp_ge_u32_e64 s[100:101], v7, v3
	v_addc_co_u32_e32 v204, vcc, 0, v204, vcc
	v_cmp_ge_u32_e32 vcc, v14, v3
	v_addc_co_u32_e64 v204, s[98:99], 0, v204, s[98:99]
	v_cmp_ge_u32_e64 s[98:99], v5, v3
	v_addc_co_u32_e64 v204, s[100:101], 0, v204, s[100:101]
	v_cmp_ge_u32_e64 s[100:101], v11, v3
	v_addc_co_u32_e32 v204, vcc, 0, v204, vcc
	v_cmp_ge_u32_e32 vcc, v4, v3
	v_addc_co_u32_e64 v204, s[98:99], 0, v204, s[98:99]
	v_cmp_ge_u32_e64 s[98:99], v22, v3
	v_addc_co_u32_e64 v204, s[100:101], 0, v204, s[100:101]
	v_cmp_ge_u32_e64 s[100:101], v21, v3
	v_addc_co_u32_e32 v204, vcc, 0, v204, vcc
	v_cmp_ge_u32_e32 vcc, v24, v3
	v_addc_co_u32_e64 v204, s[98:99], 0, v204, s[98:99]
	v_cmp_ge_u32_e64 s[98:99], v23, v3
	v_addc_co_u32_e64 v204, s[100:101], 0, v204, s[100:101]
	v_cmp_ge_u32_e64 s[100:101], v26, v3
	v_addc_co_u32_e32 v204, vcc, 0, v204, vcc
	v_cmp_ge_u32_e32 vcc, v25, v3
	v_addc_co_u32_e64 v204, s[98:99], 0, v204, s[98:99]
	v_cmp_ge_u32_e64 s[98:99], v28, v3
	v_addc_co_u32_e64 v204, s[100:101], 0, v204, s[100:101]
	v_cmp_ge_u32_e64 s[100:101], v27, v3
	v_addc_co_u32_e32 v204, vcc, 0, v204, vcc
	v_cmp_ge_u32_e32 vcc, v31, v3
	v_addc_co_u32_e64 v204, s[98:99], 0, v204, s[98:99]
	v_cmp_ge_u32_e64 s[98:99], v29, v3
	v_addc_co_u32_e64 v204, s[100:101], 0, v204, s[100:101]
	v_cmp_ge_u32_e64 s[100:101], v33, v3
	v_addc_co_u32_e32 v204, vcc, 0, v204, vcc
	v_cmp_ge_u32_e32 vcc, v32, v3
	v_addc_co_u32_e64 v204, s[98:99], 0, v204, s[98:99]
	v_cmp_ge_u32_e64 s[98:99], v35, v3
	v_addc_co_u32_e64 v204, s[100:101], 0, v204, s[100:101]
	v_cmp_ge_u32_e64 s[100:101], v34, v3
	v_addc_co_u32_e32 v204, vcc, 0, v204, vcc
	v_cmp_ge_u32_e32 vcc, v37, v3
	v_addc_co_u32_e64 v204, s[98:99], 0, v204, s[98:99]
	v_cmp_ge_u32_e64 s[98:99], v36, v3
	v_addc_co_u32_e64 v204, s[100:101], 0, v204, s[100:101]
	s_nop 1
	v_addc_co_u32_e32 v204, vcc, 0, v204, vcc
	v_addc_co_u32_e64 v204, s[98:99], 0, v204, s[98:99]
	s_nop 0
	s_cmpk_gt_u32 s3, 0x7ff
	s_cselect_b64 s[6:7], -1, 0
	s_cmpk_lt_u32 s3, 0x800
	s_cbranch_scc1 .LBB0_1331
	v_cmp_ge_u32_e64 s[100:101], v39, v3
	v_cmp_ge_u32_e32 vcc, v38, v3
	v_cmp_ge_u32_e64 s[98:99], v41, v3
	v_addc_co_u32_e64 v204, s[100:101], 0, v204, s[100:101]
	v_cmp_ge_u32_e64 s[100:101], v40, v3
	v_addc_co_u32_e32 v204, vcc, 0, v204, vcc
	v_cmp_ge_u32_e32 vcc, v43, v3
	v_addc_co_u32_e64 v204, s[98:99], 0, v204, s[98:99]
	v_cmp_ge_u32_e64 s[98:99], v42, v3
	v_addc_co_u32_e64 v204, s[100:101], 0, v204, s[100:101]
	v_cmp_ge_u32_e64 s[100:101], v45, v3
	v_addc_co_u32_e32 v204, vcc, 0, v204, vcc
	v_cmp_ge_u32_e32 vcc, v44, v3
	v_addc_co_u32_e64 v204, s[98:99], 0, v204, s[98:99]
	v_cmp_ge_u32_e64 s[98:99], v47, v3
	v_addc_co_u32_e64 v204, s[100:101], 0, v204, s[100:101]
	v_cmp_ge_u32_e64 s[100:101], v46, v3
	v_addc_co_u32_e32 v204, vcc, 0, v204, vcc
	v_cmp_ge_u32_e32 vcc, v49, v3
	v_addc_co_u32_e64 v204, s[98:99], 0, v204, s[98:99]
	v_cmp_ge_u32_e64 s[98:99], v48, v3
	v_addc_co_u32_e64 v204, s[100:101], 0, v204, s[100:101]
	v_cmp_ge_u32_e64 s[100:101], v51, v3
	v_addc_co_u32_e32 v204, vcc, 0, v204, vcc
	v_cmp_ge_u32_e32 vcc, v50, v3
	v_addc_co_u32_e64 v204, s[98:99], 0, v204, s[98:99]
	v_cmp_ge_u32_e64 s[98:99], v53, v3
	v_addc_co_u32_e64 v204, s[100:101], 0, v204, s[100:101]
	v_cmp_ge_u32_e64 s[100:101], v52, v3
	v_addc_co_u32_e32 v204, vcc, 0, v204, vcc
	s_nop 1
	v_addc_co_u32_e64 v204, s[98:99], 0, v204, s[98:99]
	v_addc_co_u32_e64 v204, s[100:101], 0, v204, s[100:101]
	s_nop 0
	s_cmpk_gt_u32 s3, 0xbff
	s_cselect_b64 s[8:9], -1, 0
	s_cmpk_lt_u32 s3, 0xc00
	s_cbranch_scc0 .LBB0_1332

.LBB0_1103:
	v_cmp_ge_u32_e32 vcc, v71, v3
	v_cmp_ge_u32_e64 s[98:99], v70, v3
	v_cmp_ge_u32_e64 s[100:101], v73, v3
	v_addc_co_u32_e32 v204, vcc, 0, v204, vcc
	v_cmp_ge_u32_e32 vcc, v72, v3
	v_addc_co_u32_e64 v204, s[98:99], 0, v204, s[98:99]
	v_cmp_ge_u32_e64 s[98:99], v75, v3
	v_addc_co_u32_e64 v204, s[100:101], 0, v204, s[100:101]
	v_cmp_ge_u32_e64 s[100:101], v74, v3
	v_addc_co_u32_e32 v204, vcc, 0, v204, vcc
	v_cmp_ge_u32_e32 vcc, v77, v3
	v_addc_co_u32_e64 v204, s[98:99], 0, v204, s[98:99]
	v_cmp_ge_u32_e64 s[98:99], v76, v3
	v_addc_co_u32_e64 v204, s[100:101], 0, v204, s[100:101]
	v_cmp_ge_u32_e64 s[100:101], v79, v3
	v_addc_co_u32_e32 v204, vcc, 0, v204, vcc
	v_cmp_ge_u32_e32 vcc, v78, v3
	v_addc_co_u32_e64 v204, s[98:99], 0, v204, s[98:99]
	v_cmp_ge_u32_e64 s[98:99], v81, v3
	v_addc_co_u32_e64 v204, s[100:101], 0, v204, s[100:101]
	v_cmp_ge_u32_e64 s[100:101], v80, v3
	v_addc_co_u32_e32 v204, vcc, 0, v204, vcc
	v_cmp_ge_u32_e32 vcc, v83, v3
	v_addc_co_u32_e64 v204, s[98:99], 0, v204, s[98:99]
	v_cmp_ge_u32_e64 s[98:99], v82, v3
	v_addc_co_u32_e64 v204, s[100:101], 0, v204, s[100:101]
	v_cmp_ge_u32_e64 s[100:101], v85, v3
	v_addc_co_u32_e32 v204, vcc, 0, v204, vcc
	v_cmp_ge_u32_e32 vcc, v84, v3
	v_addc_co_u32_e64 v204, s[98:99], 0, v204, s[98:99]
	s_nop 1
	v_addc_co_u32_e64 v204, s[100:101], 0, v204, s[100:101]
	v_addc_co_u32_e32 v204, vcc, 0, v204, vcc
	s_nop 0
	s_cmpk_gt_u32 s3, 0x13ff
	s_cselect_b64 s[12:13], -1, 0
	s_cmpk_lt_u32 s3, 0x1400
	s_cbranch_scc0 .LBB0_1334

.LBB0_1105:
	v_cmp_ge_u32_e64 s[98:99], v103, v3
	v_cmp_ge_u32_e64 s[100:101], v102, v3
	v_cmp_ge_u32_e32 vcc, v105, v3
	v_addc_co_u32_e64 v204, s[98:99], 0, v204, s[98:99]
	v_cmp_ge_u32_e64 s[98:99], v104, v3
	v_addc_co_u32_e64 v204, s[100:101], 0, v204, s[100:101]
	v_cmp_ge_u32_e64 s[100:101], v107, v3
	v_addc_co_u32_e32 v204, vcc, 0, v204, vcc
	v_cmp_ge_u32_e32 vcc, v106, v3
	v_addc_co_u32_e64 v204, s[98:99], 0, v204, s[98:99]
	v_cmp_ge_u32_e64 s[98:99], v109, v3
	v_addc_co_u32_e64 v204, s[100:101], 0, v204, s[100:101]
	v_cmp_ge_u32_e64 s[100:101], v108, v3
	v_addc_co_u32_e32 v204, vcc, 0, v204, vcc
	v_cmp_ge_u32_e32 vcc, v111, v3
	v_addc_co_u32_e64 v204, s[98:99], 0, v204, s[98:99]
	v_cmp_ge_u32_e64 s[98:99], v110, v3
	v_addc_co_u32_e64 v204, s[100:101], 0, v204, s[100:101]
	v_cmp_ge_u32_e64 s[100:101], v113, v3
	v_addc_co_u32_e32 v204, vcc, 0, v204, vcc
	v_cmp_ge_u32_e32 vcc, v112, v3
	v_addc_co_u32_e64 v204, s[98:99], 0, v204, s[98:99]
	v_cmp_ge_u32_e64 s[98:99], v115, v3
	v_addc_co_u32_e64 v204, s[100:101], 0, v204, s[100:101]
	v_cmp_ge_u32_e64 s[100:101], v114, v3
	v_addc_co_u32_e32 v204, vcc, 0, v204, vcc
	v_cmp_ge_u32_e32 vcc, v117, v3
	v_addc_co_u32_e64 v204, s[98:99], 0, v204, s[98:99]
	v_cmp_ge_u32_e64 s[98:99], v116, v3
	v_addc_co_u32_e64 v204, s[100:101], 0, v204, s[100:101]
	s_nop 1
	v_addc_co_u32_e32 v204, vcc, 0, v204, vcc
	v_addc_co_u32_e64 v204, s[98:99], 0, v204, s[98:99]
	s_nop 0
	s_cmpk_gt_u32 s3, 0x1bff
	s_cselect_b64 s[18:19], -1, 0
	s_cmpk_lt_u32 s3, 0x1c00
	s_cbranch_scc0 .LBB0_1336
	s_branch .LBB0_1337

.LBB0_1109:
	s_cmp_gt_i32 s30, -1
	s_cselect_b64 s[6:7], -1, 0
	s_xor_b64 s[8:9], s[14:15], -1
	s_and_b64 s[6:7], s[8:9], s[6:7]
	s_sub_i32 s4, s24, s5
	s_cmpk_gt_i32 s4, 0x200
	s_cselect_b64 s[8:9], -1, 0
	s_and_b64 s[6:7], s[6:7], s[8:9]
	s_andn2_b64 vcc, exec, s[6:7]
	s_mov_b64 s[6:7], -1
	s_cbranch_vccnz .LBB0_1108
	v_lshl_or_b32 v3, 1, s30, v2
	s_waitcnt vmcnt(0) lgkmcnt(0)
	v_mov_b32_e32 v204, 0
	v_cmp_ge_u32_e32 vcc, v19, v3
	v_cmp_ge_u32_e64 s[98:99], v13, v3
	v_cmp_ge_u32_e64 s[100:101], v20, v3
	v_addc_co_u32_e32 v204, vcc, 0, v204, vcc
	v_cmp_ge_u32_e32 vcc, v12, v3
	v_addc_co_u32_e64 v204, s[98:99], 0, v204, s[98:99]
	v_cmp_ge_u32_e64 s[98:99], v18, v3
	v_addc_co_u32_e64 v204, s[100:101], 0, v204, s[100:101]
	v_cmp_ge_u32_e64 s[100:101], v10, v3
	v_addc_co_u32_e32 v204, vcc, 0, v204, vcc
	v_cmp_ge_u32_e32 vcc, v17, v3
	v_addc_co_u32_e64 v204, s[98:99], 0, v204, s[98:99]
	v_cmp_ge_u32_e64 s[98:99], v9, v3
	v_addc_co_u32_e64 v204, s[100:101], 0, v204, s[100:101]
	v_cmp_ge_u32_e64 s[100:101], v16, v3
	v_addc_co_u32_e32 v204, vcc, 0, v204, vcc
	v_cmp_ge_u32_e32 vcc, v8, v3
	v_addc_co_u32_e64 v204, s[98:99], 0, v204, s[98:99]
	v_cmp_ge_u32_e64 s[98:99], v15, v3
	v_addc_co_u32_e64 v204, s[100:101], 0, v204, s[100:101]
	v_cmp_ge_u32_e64 s[100:101], v7, v3
	v_addc_co_u32_e32 v204, vcc, 0, v204, vcc
	v_cmp_ge_u32_e32 vcc, v14, v3
	v_addc_co_u32_e64 v204, s[98:99], 0, v204, s[98:99]
	v_cmp_ge_u32_e64 s[98:99], v5, v3
	v_addc_co_u32_e64 v204, s[100:101], 0, v204, s[100:101]
	v_cmp_ge_u32_e64 s[100:101], v11, v3
	v_addc_co_u32_e32 v204, vcc, 0, v204, vcc
	v_cmp_ge_u32_e32 vcc, v4, v3
	v_addc_co_u32_e64 v204, s[98:99], 0, v204, s[98:99]
	s_nop 1
	v_addc_co_u32_e64 v204, s[100:101], 0, v204, s[100:101]
	v_addc_co_u32_e32 v204, vcc, 0, v204, vcc
	s_nop 0
	s_andn2_b64 vcc, exec, s[88:89]
	s_cbranch_vccnz .LBB0_1119
	v_cmp_ge_u32_e64 s[98:99], v22, v3
	v_cmp_ge_u32_e64 s[100:101], v21, v3
	v_cmp_ge_u32_e32 vcc, v24, v3
	v_addc_co_u32_e64 v204, s[98:99], 0, v204, s[98:99]
	v_cmp_ge_u32_e64 s[98:99], v23, v3
	v_addc_co_u32_e64 v204, s[100:101], 0, v204, s[100:101]
	v_cmp_ge_u32_e64 s[100:101], v26, v3
	v_addc_co_u32_e32 v204, vcc, 0, v204, vcc
	v_cmp_ge_u32_e32 vcc, v25, v3
	v_addc_co_u32_e64 v204, s[98:99], 0, v204, s[98:99]
	v_cmp_ge_u32_e64 s[98:99], v28, v3
	v_addc_co_u32_e64 v204, s[100:101], 0, v204, s[100:101]
	v_cmp_ge_u32_e64 s[100:101], v27, v3
	v_addc_co_u32_e32 v204, vcc, 0, v204, vcc
	v_cmp_ge_u32_e32 vcc, v31, v3
	v_addc_co_u32_e64 v204, s[98:99], 0, v204, s[98:99]
	v_cmp_ge_u32_e64 s[98:99], v29, v3
	v_addc_co_u32_e64 v204, s[100:101], 0, v204, s[100:101]
	v_cmp_ge_u32_e64 s[100:101], v33, v3
	v_addc_co_u32_e32 v204, vcc, 0, v204, vcc
	v_cmp_ge_u32_e32 vcc, v32, v3
	v_addc_co_u32_e64 v204, s[98:99], 0, v204, s[98:99]
	v_cmp_ge_u32_e64 s[98:99], v35, v3
	v_addc_co_u32_e64 v204, s[100:101], 0, v204, s[100:101]
	v_cmp_ge_u32_e64 s[100:101], v34, v3
	v_addc_co_u32_e32 v204, vcc, 0, v204, vcc
	v_cmp_ge_u32_e32 vcc, v37, v3
	v_addc_co_u32_e64 v204, s[98:99], 0, v204, s[98:99]
	v_cmp_ge_u32_e64 s[98:99], v36, v3
	v_addc_co_u32_e64 v204, s[100:101], 0, v204, s[100:101]
	s_nop 1
	v_addc_co_u32_e32 v204, vcc, 0, v204, vcc
	v_addc_co_u32_e64 v204, s[98:99], 0, v204, s[98:99]
	s_nop 0
	s_andn2_b64 vcc, exec, s[66:67]
	s_cbranch_vccz .LBB0_1120

.LBB0_1113:
	v_cmp_ge_u32_e64 s[100:101], v55, v3
	v_cmp_ge_u32_e32 vcc, v54, v3
	v_cmp_ge_u32_e64 s[98:99], v57, v3
	v_addc_co_u32_e64 v204, s[100:101], 0, v204, s[100:101]
	v_cmp_ge_u32_e64 s[100:101], v56, v3
	v_addc_co_u32_e32 v204, vcc, 0, v204, vcc
	v_cmp_ge_u32_e32 vcc, v59, v3
	v_addc_co_u32_e64 v204, s[98:99], 0, v204, s[98:99]
	v_cmp_ge_u32_e64 s[98:99], v58, v3
	v_addc_co_u32_e64 v204, s[100:101], 0, v204, s[100:101]
	v_cmp_ge_u32_e64 s[100:101], v61, v3
	v_addc_co_u32_e32 v204, vcc, 0, v204, vcc
	v_cmp_ge_u32_e32 vcc, v60, v3
	v_addc_co_u32_e64 v204, s[98:99], 0, v204, s[98:99]
	v_cmp_ge_u32_e64 s[98:99], v63, v3
	v_addc_co_u32_e64 v204, s[100:101], 0, v204, s[100:101]
	v_cmp_ge_u32_e64 s[100:101], v62, v3
	v_addc_co_u32_e32 v204, vcc, 0, v204, vcc
	v_cmp_ge_u32_e32 vcc, v65, v3
	v_addc_co_u32_e64 v204, s[98:99], 0, v204, s[98:99]
	v_cmp_ge_u32_e64 s[98:99], v64, v3
	v_addc_co_u32_e64 v204, s[100:101], 0, v204, s[100:101]
	v_cmp_ge_u32_e64 s[100:101], v67, v3
	v_addc_co_u32_e32 v204, vcc, 0, v204, vcc
	v_cmp_ge_u32_e32 vcc, v66, v3
	v_addc_co_u32_e64 v204, s[98:99], 0, v204, s[98:99]
	v_cmp_ge_u32_e64 s[98:99], v69, v3
	v_addc_co_u32_e64 v204, s[100:101], 0, v204, s[100:101]
	v_cmp_ge_u32_e64 s[100:101], v68, v3
	v_addc_co_u32_e32 v204, vcc, 0, v204, vcc
	s_nop 1
	v_addc_co_u32_e64 v204, s[98:99], 0, v204, s[98:99]
	v_addc_co_u32_e64 v204, s[100:101], 0, v204, s[100:101]
	s_nop 0
	s_andn2_b64 vcc, exec, s[62:63]
	s_cbranch_vccz .LBB0_1122

.LBB0_1115:
	v_cmp_ge_u32_e32 vcc, v87, v3
	v_cmp_ge_u32_e64 s[98:99], v86, v3
	v_cmp_ge_u32_e64 s[100:101], v89, v3
	v_addc_co_u32_e32 v204, vcc, 0, v204, vcc
	v_cmp_ge_u32_e32 vcc, v88, v3
	v_addc_co_u32_e64 v204, s[98:99], 0, v204, s[98:99]
	v_cmp_ge_u32_e64 s[98:99], v91, v3
	v_addc_co_u32_e64 v204, s[100:101], 0, v204, s[100:101]
	v_cmp_ge_u32_e64 s[100:101], v90, v3
	v_addc_co_u32_e32 v204, vcc, 0, v204, vcc
	v_cmp_ge_u32_e32 vcc, v93, v3
	v_addc_co_u32_e64 v204, s[98:99], 0, v204, s[98:99]
	v_cmp_ge_u32_e64 s[98:99], v92, v3
	v_addc_co_u32_e64 v204, s[100:101], 0, v204, s[100:101]
	v_cmp_ge_u32_e64 s[100:101], v95, v3
	v_addc_co_u32_e32 v204, vcc, 0, v204, vcc
	v_cmp_ge_u32_e32 vcc, v94, v3
	v_addc_co_u32_e64 v204, s[98:99], 0, v204, s[98:99]
	v_cmp_ge_u32_e64 s[98:99], v97, v3
	v_addc_co_u32_e64 v204, s[100:101], 0, v204, s[100:101]
	v_cmp_ge_u32_e64 s[100:101], v96, v3
	v_addc_co_u32_e32 v204, vcc, 0, v204, vcc
	v_cmp_ge_u32_e32 vcc, v99, v3
	v_addc_co_u32_e64 v204, s[98:99], 0, v204, s[98:99]
	v_cmp_ge_u32_e64 s[98:99], v98, v3
	v_addc_co_u32_e64 v204, s[100:101], 0, v204, s[100:101]
	v_cmp_ge_u32_e64 s[100:101], v101, v3
	v_addc_co_u32_e32 v204, vcc, 0, v204, vcc
	v_cmp_ge_u32_e32 vcc, v100, v3
	v_addc_co_u32_e64 v204, s[98:99], 0, v204, s[98:99]
	s_nop 1
	v_addc_co_u32_e64 v204, s[100:101], 0, v204, s[100:101]
	v_addc_co_u32_e32 v204, vcc, 0, v204, vcc
	s_nop 0
	s_andn2_b64 vcc, exec, s[58:59]
	s_cbranch_vccz .LBB0_1124

.LBB0_1117:
	v_cmp_ge_u32_e64 s[98:99], v119, v3
	v_cmp_ge_u32_e64 s[100:101], v118, v3
	v_cmp_ge_u32_e32 vcc, v123, v3
	v_addc_co_u32_e64 v204, s[98:99], 0, v204, s[98:99]
	v_cmp_ge_u32_e64 s[98:99], v120, v3
	v_addc_co_u32_e64 v204, s[100:101], 0, v204, s[100:101]
	v_cmp_ge_u32_e64 s[100:101], v125, v3
	v_addc_co_u32_e32 v204, vcc, 0, v204, vcc
	v_cmp_ge_u32_e32 vcc, v121, v3
	v_addc_co_u32_e64 v204, s[98:99], 0, v204, s[98:99]
	v_cmp_ge_u32_e64 s[98:99], v127, v3
	v_addc_co_u32_e64 v204, s[100:101], 0, v204, s[100:101]
	v_cmp_ge_u32_e64 s[100:101], v122, v3
	v_addc_co_u32_e32 v204, vcc, 0, v204, vcc
	v_cmp_ge_u32_e32 vcc, v129, v3
	v_addc_co_u32_e64 v204, s[98:99], 0, v204, s[98:99]
	v_cmp_ge_u32_e64 s[98:99], v124, v3
	v_addc_co_u32_e64 v204, s[100:101], 0, v204, s[100:101]
	v_cmp_ge_u32_e64 s[100:101], v131, v3
	v_addc_co_u32_e32 v204, vcc, 0, v204, vcc
	v_cmp_ge_u32_e32 vcc, v126, v3
	v_addc_co_u32_e64 v204, s[98:99], 0, v204, s[98:99]
	v_cmp_ge_u32_e64 s[98:99], v132, v3
	v_addc_co_u32_e64 v204, s[100:101], 0, v204, s[100:101]
	v_cmp_ge_u32_e64 s[100:101], v128, v3
	v_addc_co_u32_e32 v204, vcc, 0, v204, vcc
	v_cmp_ge_u32_e32 vcc, v133, v3
	v_addc_co_u32_e64 v204, s[98:99], 0, v204, s[98:99]
	v_cmp_ge_u32_e64 s[98:99], v130, v3
	v_addc_co_u32_e64 v204, s[100:101], 0, v204, s[100:101]
	s_nop 1
	v_addc_co_u32_e32 v204, vcc, 0, v204, vcc
	v_addc_co_u32_e64 v204, s[98:99], 0, v204, s[98:99]
	s_nop 0
	s_nop 1
	v_add_u32_dpp v205, v204, v204 quad_perm:[1,0,3,2] row_mask:0xf bank_mask:0xf
	s_nop 1
	v_add_u32_dpp v205, v205, v205 quad_perm:[2,3,0,1] row_mask:0xf bank_mask:0xf
	s_nop 1
	v_add_u32_dpp v205, v205, v205 row_half_mirror row_mask:0xf bank_mask:0xf
	s_nop 1
	v_add_u32_dpp v205, v205, v205 row_mirror row_mask:0xf bank_mask:0xf
	s_nop 1
	v_readlane_b32 s98, v205, 0
	v_readlane_b32 s99, v205, 16
	v_readlane_b32 s100, v205, 32
	v_readlane_b32 s101, v205, 48
	s_add_i32 s98, s98, s99
	s_add_i32 s100, s100, s101
	s_add_i32 s4, s98, s100
	s_cmpk_lt_u32 s4, 0x100
	s_cbranch_scc0 .LBB0_1126

.LBB0_1120:
	v_cmp_ge_u32_e64 s[100:101], v39, v3
	v_cmp_ge_u32_e32 vcc, v38, v3
	v_cmp_ge_u32_e64 s[98:99], v41, v3
	v_addc_co_u32_e64 v204, s[100:101], 0, v204, s[100:101]
	v_cmp_ge_u32_e64 s[100:101], v40, v3
	v_addc_co_u32_e32 v204, vcc, 0, v204, vcc
	v_cmp_ge_u32_e32 vcc, v43, v3
	v_addc_co_u32_e64 v204, s[98:99], 0, v204, s[98:99]
	v_cmp_ge_u32_e64 s[98:99], v42, v3
	v_addc_co_u32_e64 v204, s[100:101], 0, v204, s[100:101]
	v_cmp_ge_u32_e64 s[100:101], v45, v3
	v_addc_co_u32_e32 v204, vcc, 0, v204, vcc
	v_cmp_ge_u32_e32 vcc, v44, v3
	v_addc_co_u32_e64 v204, s[98:99], 0, v204, s[98:99]
	v_cmp_ge_u32_e64 s[98:99], v47, v3
	v_addc_co_u32_e64 v204, s[100:101], 0, v204, s[100:101]
	v_cmp_ge_u32_e64 s[100:101], v46, v3
	v_addc_co_u32_e32 v204, vcc, 0, v204, vcc
	v_cmp_ge_u32_e32 vcc, v49, v3
	v_addc_co_u32_e64 v204, s[98:99], 0, v204, s[98:99]
	v_cmp_ge_u32_e64 s[98:99], v48, v3
	v_addc_co_u32_e64 v204, s[100:101], 0, v204, s[100:101]
	v_cmp_ge_u32_e64 s[100:101], v51, v3
	v_addc_co_u32_e32 v204, vcc, 0, v204, vcc
	v_cmp_ge_u32_e32 vcc, v50, v3
	v_addc_co_u32_e64 v204, s[98:99], 0, v204, s[98:99]
	v_cmp_ge_u32_e64 s[98:99], v53, v3
	v_addc_co_u32_e64 v204, s[100:101], 0, v204, s[100:101]
	v_cmp_ge_u32_e64 s[100:101], v52, v3
	v_addc_co_u32_e32 v204, vcc, 0, v204, vcc
	s_nop 1
	v_addc_co_u32_e64 v204, s[98:99], 0, v204, s[98:99]
	v_addc_co_u32_e64 v204, s[100:101], 0, v204, s[100:101]
	s_nop 0
	s_andn2_b64 vcc, exec, s[64:65]
	s_cbranch_vccz .LBB0_1113

.LBB0_1122:
	v_cmp_ge_u32_e32 vcc, v71, v3
	v_cmp_ge_u32_e64 s[98:99], v70, v3
	v_cmp_ge_u32_e64 s[100:101], v73, v3
	v_addc_co_u32_e32 v204, vcc, 0, v204, vcc
	v_cmp_ge_u32_e32 vcc, v72, v3
	v_addc_co_u32_e64 v204, s[98:99], 0, v204, s[98:99]
	v_cmp_ge_u32_e64 s[98:99], v75, v3
	v_addc_co_u32_e64 v204, s[100:101], 0, v204, s[100:101]
	v_cmp_ge_u32_e64 s[100:101], v74, v3
	v_addc_co_u32_e32 v204, vcc, 0, v204, vcc
	v_cmp_ge_u32_e32 vcc, v77, v3
	v_addc_co_u32_e64 v204, s[98:99], 0, v204, s[98:99]
	v_cmp_ge_u32_e64 s[98:99], v76, v3
	v_addc_co_u32_e64 v204, s[100:101], 0, v204, s[100:101]
	v_cmp_ge_u32_e64 s[100:101], v79, v3
	v_addc_co_u32_e32 v204, vcc, 0, v204, vcc
	v_cmp_ge_u32_e32 vcc, v78, v3
	v_addc_co_u32_e64 v204, s[98:99], 0, v204, s[98:99]
	v_cmp_ge_u32_e64 s[98:99], v81, v3
	v_addc_co_u32_e64 v204, s[100:101], 0, v204, s[100:101]
	v_cmp_ge_u32_e64 s[100:101], v80, v3
	v_addc_co_u32_e32 v204, vcc, 0, v204, vcc
	v_cmp_ge_u32_e32 vcc, v83, v3
	v_addc_co_u32_e64 v204, s[98:99], 0, v204, s[98:99]
	v_cmp_ge_u32_e64 s[98:99], v82, v3
	v_addc_co_u32_e64 v204, s[100:101], 0, v204, s[100:101]
	v_cmp_ge_u32_e64 s[100:101], v85, v3
	v_addc_co_u32_e32 v204, vcc, 0, v204, vcc
	v_cmp_ge_u32_e32 vcc, v84, v3
	v_addc_co_u32_e64 v204, s[98:99], 0, v204, s[98:99]
	s_nop 1
	v_addc_co_u32_e64 v204, s[100:101], 0, v204, s[100:101]
	v_addc_co_u32_e32 v204, vcc, 0, v204, vcc
	s_nop 0
	s_andn2_b64 vcc, exec, s[60:61]
	s_cbranch_vccz .LBB0_1115

.LBB0_1124:
	v_cmp_ge_u32_e64 s[98:99], v103, v3
	v_cmp_ge_u32_e64 s[100:101], v102, v3
	v_cmp_ge_u32_e32 vcc, v105, v3
	v_addc_co_u32_e64 v204, s[98:99], 0, v204, s[98:99]
	v_cmp_ge_u32_e64 s[98:99], v104, v3
	v_addc_co_u32_e64 v204, s[100:101], 0, v204, s[100:101]
	v_cmp_ge_u32_e64 s[100:101], v107, v3
	v_addc_co_u32_e32 v204, vcc, 0, v204, vcc
	v_cmp_ge_u32_e32 vcc, v106, v3
	v_addc_co_u32_e64 v204, s[98:99], 0, v204, s[98:99]
	v_cmp_ge_u32_e64 s[98:99], v109, v3
	v_addc_co_u32_e64 v204, s[100:101], 0, v204, s[100:101]
	v_cmp_ge_u32_e64 s[100:101], v108, v3
	v_addc_co_u32_e32 v204, vcc, 0, v204, vcc
	v_cmp_ge_u32_e32 vcc, v111, v3
	v_addc_co_u32_e64 v204, s[98:99], 0, v204, s[98:99]
	v_cmp_ge_u32_e64 s[98:99], v110, v3
	v_addc_co_u32_e64 v204, s[100:101], 0, v204, s[100:101]
	v_cmp_ge_u32_e64 s[100:101], v113, v3
	v_addc_co_u32_e32 v204, vcc, 0, v204, vcc
	v_cmp_ge_u32_e32 vcc, v112, v3
	v_addc_co_u32_e64 v204, s[98:99], 0, v204, s[98:99]
	v_cmp_ge_u32_e64 s[98:99], v115, v3
	v_addc_co_u32_e64 v204, s[100:101], 0, v204, s[100:101]
	v_cmp_ge_u32_e64 s[100:101], v114, v3
	v_addc_co_u32_e32 v204, vcc, 0, v204, vcc
	v_cmp_ge_u32_e32 vcc, v117, v3
	v_addc_co_u32_e64 v204, s[98:99], 0, v204, s[98:99]
	v_cmp_ge_u32_e64 s[98:99], v116, v3
	v_addc_co_u32_e64 v204, s[100:101], 0, v204, s[100:101]
	s_nop 1
	v_addc_co_u32_e32 v204, vcc, 0, v204, vcc
	v_addc_co_u32_e64 v204, s[98:99], 0, v204, s[98:99]
	s_nop 0
	s_andn2_b64 vcc, exec, s[56:57]
	s_cbranch_vccz .LBB0_1117
.LBB0_1125:
	s_nop 1
	v_add_u32_dpp v205, v204, v204 quad_perm:[1,0,3,2] row_mask:0xf bank_mask:0xf
	s_nop 1
	v_add_u32_dpp v205, v205, v205 quad_perm:[2,3,0,1] row_mask:0xf bank_mask:0xf
	s_nop 1
	v_add_u32_dpp v205, v205, v205 row_half_mirror row_mask:0xf bank_mask:0xf
	s_nop 1
	v_add_u32_dpp v205, v205, v205 row_mirror row_mask:0xf bank_mask:0xf
	s_nop 1
	v_readlane_b32 s98, v205, 0
	v_readlane_b32 s99, v205, 16
	v_readlane_b32 s100, v205, 32
	v_readlane_b32 s101, v205, 48
	s_add_i32 s98, s98, s99
	s_add_i32 s100, s100, s101
	s_add_i32 s4, s98, s100
	s_cmpk_lt_u32 s4, 0x100
	s_cbranch_scc1 .LBB0_1118

.LBB0_1332:
	v_cmp_ge_u32_e64 s[100:101], v55, v3
	v_cmp_ge_u32_e32 vcc, v54, v3
	v_cmp_ge_u32_e64 s[98:99], v57, v3
	v_addc_co_u32_e64 v204, s[100:101], 0, v204, s[100:101]
	v_cmp_ge_u32_e64 s[100:101], v56, v3
	v_addc_co_u32_e32 v204, vcc, 0, v204, vcc
	v_cmp_ge_u32_e32 vcc, v59, v3
	v_addc_co_u32_e64 v204, s[98:99], 0, v204, s[98:99]
	v_cmp_ge_u32_e64 s[98:99], v58, v3
	v_addc_co_u32_e64 v204, s[100:101], 0, v204, s[100:101]
	v_cmp_ge_u32_e64 s[100:101], v61, v3
	v_addc_co_u32_e32 v204, vcc, 0, v204, vcc
	v_cmp_ge_u32_e32 vcc, v60, v3
	v_addc_co_u32_e64 v204, s[98:99], 0, v204, s[98:99]
	v_cmp_ge_u32_e64 s[98:99], v63, v3
	v_addc_co_u32_e64 v204, s[100:101], 0, v204, s[100:101]
	v_cmp_ge_u32_e64 s[100:101], v62, v3
	v_addc_co_u32_e32 v204, vcc, 0, v204, vcc
	v_cmp_ge_u32_e32 vcc, v65, v3
	v_addc_co_u32_e64 v204, s[98:99], 0, v204, s[98:99]
	v_cmp_ge_u32_e64 s[98:99], v64, v3
	v_addc_co_u32_e64 v204, s[100:101], 0, v204, s[100:101]
	v_cmp_ge_u32_e64 s[100:101], v67, v3
	v_addc_co_u32_e32 v204, vcc, 0, v204, vcc
	v_cmp_ge_u32_e32 vcc, v66, v3
	v_addc_co_u32_e64 v204, s[98:99], 0, v204, s[98:99]
	v_cmp_ge_u32_e64 s[98:99], v69, v3
	v_addc_co_u32_e64 v204, s[100:101], 0, v204, s[100:101]
	v_cmp_ge_u32_e64 s[100:101], v68, v3
	v_addc_co_u32_e32 v204, vcc, 0, v204, vcc
	s_nop 1
	v_addc_co_u32_e64 v204, s[98:99], 0, v204, s[98:99]
	v_addc_co_u32_e64 v204, s[100:101], 0, v204, s[100:101]
	s_nop 0
	s_cmpk_gt_u32 s3, 0xfff
	s_cselect_b64 s[10:11], -1, 0
	s_cmpk_lt_u32 s3, 0x1000
	s_cbranch_scc0 .LBB0_1103

.LBB0_1334:
	v_cmp_ge_u32_e32 vcc, v87, v3
	v_cmp_ge_u32_e64 s[98:99], v86, v3
	v_cmp_ge_u32_e64 s[100:101], v89, v3
	v_addc_co_u32_e32 v204, vcc, 0, v204, vcc
	v_cmp_ge_u32_e32 vcc, v88, v3
	v_addc_co_u32_e64 v204, s[98:99], 0, v204, s[98:99]
	v_cmp_ge_u32_e64 s[98:99], v91, v3
	v_addc_co_u32_e64 v204, s[100:101], 0, v204, s[100:101]
	v_cmp_ge_u32_e64 s[100:101], v90, v3
	v_addc_co_u32_e32 v204, vcc, 0, v204, vcc
	v_cmp_ge_u32_e32 vcc, v93, v3
	v_addc_co_u32_e64 v204, s[98:99], 0, v204, s[98:99]
	v_cmp_ge_u32_e64 s[98:99], v92, v3
	v_addc_co_u32_e64 v204, s[100:101], 0, v204, s[100:101]
	v_cmp_ge_u32_e64 s[100:101], v95, v3
	v_addc_co_u32_e32 v204, vcc, 0, v204, vcc
	v_cmp_ge_u32_e32 vcc, v94, v3
	v_addc_co_u32_e64 v204, s[98:99], 0, v204, s[98:99]
	v_cmp_ge_u32_e64 s[98:99], v97, v3
	v_addc_co_u32_e64 v204, s[100:101], 0, v204, s[100:101]
	v_cmp_ge_u32_e64 s[100:101], v96, v3
	v_addc_co_u32_e32 v204, vcc, 0, v204, vcc
	v_cmp_ge_u32_e32 vcc, v99, v3
	v_addc_co_u32_e64 v204, s[98:99], 0, v204, s[98:99]
	v_cmp_ge_u32_e64 s[98:99], v98, v3
	v_addc_co_u32_e64 v204, s[100:101], 0, v204, s[100:101]
	v_cmp_ge_u32_e64 s[100:101], v101, v3
	v_addc_co_u32_e32 v204, vcc, 0, v204, vcc
	v_cmp_ge_u32_e32 vcc, v100, v3
	v_addc_co_u32_e64 v204, s[98:99], 0, v204, s[98:99]
	s_nop 1
	v_addc_co_u32_e64 v204, s[100:101], 0, v204, s[100:101]
	v_addc_co_u32_e32 v204, vcc, 0, v204, vcc
	s_nop 0
	s_cmpk_gt_u32 s3, 0x17ff
	s_cselect_b64 s[16:17], -1, 0
	s_cmpk_lt_u32 s3, 0x1800
	s_cbranch_scc0 .LBB0_1105

.LBB0_1336:
	v_cmp_ge_u32_e64 s[98:99], v119, v3
	v_cmp_ge_u32_e64 s[100:101], v118, v3
	v_cmp_ge_u32_e32 vcc, v123, v3
	v_addc_co_u32_e64 v204, s[98:99], 0, v204, s[98:99]
	v_cmp_ge_u32_e64 s[98:99], v120, v3
	v_addc_co_u32_e64 v204, s[100:101], 0, v204, s[100:101]
	v_cmp_ge_u32_e64 s[100:101], v125, v3
	v_addc_co_u32_e32 v204, vcc, 0, v204, vcc
	v_cmp_ge_u32_e32 vcc, v121, v3
	v_addc_co_u32_e64 v204, s[98:99], 0, v204, s[98:99]
	v_cmp_ge_u32_e64 s[98:99], v127, v3
	v_addc_co_u32_e64 v204, s[100:101], 0, v204, s[100:101]
	v_cmp_ge_u32_e64 s[100:101], v122, v3
	v_addc_co_u32_e32 v204, vcc, 0, v204, vcc
	v_cmp_ge_u32_e32 vcc, v129, v3
	v_addc_co_u32_e64 v204, s[98:99], 0, v204, s[98:99]
	v_cmp_ge_u32_e64 s[98:99], v124, v3
	v_addc_co_u32_e64 v204, s[100:101], 0, v204, s[100:101]
	v_cmp_ge_u32_e64 s[100:101], v131, v3
	v_addc_co_u32_e32 v204, vcc, 0, v204, vcc
	v_cmp_ge_u32_e32 vcc, v126, v3
	v_addc_co_u32_e64 v204, s[98:99], 0, v204, s[98:99]
	v_cmp_ge_u32_e64 s[98:99], v132, v3
	v_addc_co_u32_e64 v204, s[100:101], 0, v204, s[100:101]
	v_cmp_ge_u32_e64 s[100:101], v128, v3
	v_addc_co_u32_e32 v204, vcc, 0, v204, vcc
	v_cmp_ge_u32_e32 vcc, v133, v3
	v_addc_co_u32_e64 v204, s[98:99], 0, v204, s[98:99]
	v_cmp_ge_u32_e64 s[98:99], v130, v3
	v_addc_co_u32_e64 v204, s[100:101], 0, v204, s[100:101]
	s_nop 1
	v_addc_co_u32_e32 v204, vcc, 0, v204, vcc
	v_addc_co_u32_e64 v204, s[98:99], 0, v204, s[98:99]
	s_nop 0
.LBB0_1337:
	s_nop 1
	v_add_u32_dpp v205, v204, v204 quad_perm:[1,0,3,2] row_mask:0xf bank_mask:0xf
	s_nop 1
	v_add_u32_dpp v205, v205, v205 quad_perm:[2,3,0,1] row_mask:0xf bank_mask:0xf
	s_nop 1
	v_add_u32_dpp v205, v205, v205 row_half_mirror row_mask:0xf bank_mask:0xf
	s_nop 1
	v_add_u32_dpp v205, v205, v205 row_mirror row_mask:0xf bank_mask:0xf
	s_nop 1
	v_readlane_b32 s98, v205, 0
	v_readlane_b32 s99, v205, 16
	v_readlane_b32 s100, v205, 32
	v_readlane_b32 s101, v205, 48
	s_add_i32 s98, s98, s99
	s_add_i32 s100, s100, s101
	s_add_i32 s4, s98, s100
	s_cmpk_lt_u32 s4, 0x100
	s_cselect_b64 s[20:21], -1, 0
	s_cmpk_gt_u32 s4, 0xff
	s_mov_b32 s5, 0x800000
	s_cselect_b32 s26, s5, 0xff800000
	s_mov_b64 s[14:15], 0
	s_mov_b32 s30, 31
	v_mov_b32_e32 v134, 0
	s_mov_b32 s28, 0
	s_mov_b32 s27, 0
	s_mov_b32 s29, s74
.LBB0_1338:
	v_add_u32_e32 v135, s26, v3
	v_mov_b32_e32 v204, 0
	v_cmp_ge_u32_e32 vcc, v19, v135
	v_cmp_ge_u32_e64 s[98:99], v13, v135
	v_cmp_ge_u32_e64 s[100:101], v20, v135
	v_addc_co_u32_e32 v204, vcc, 0, v204, vcc
	v_cmp_ge_u32_e32 vcc, v12, v135
	v_addc_co_u32_e64 v204, s[98:99], 0, v204, s[98:99]
	v_cmp_ge_u32_e64 s[98:99], v18, v135
	v_addc_co_u32_e64 v204, s[100:101], 0, v204, s[100:101]
	v_cmp_ge_u32_e64 s[100:101], v10, v135
	v_addc_co_u32_e32 v204, vcc, 0, v204, vcc
	v_cmp_ge_u32_e32 vcc, v17, v135
	v_addc_co_u32_e64 v204, s[98:99], 0, v204, s[98:99]
	v_cmp_ge_u32_e64 s[98:99], v9, v135
	v_addc_co_u32_e64 v204, s[100:101], 0, v204, s[100:101]
	v_cmp_ge_u32_e64 s[100:101], v16, v135
	v_addc_co_u32_e32 v204, vcc, 0, v204, vcc
	v_cmp_ge_u32_e32 vcc, v8, v135
	v_addc_co_u32_e64 v204, s[98:99], 0, v204, s[98:99]
	v_cmp_ge_u32_e64 s[98:99], v15, v135
	v_addc_co_u32_e64 v204, s[100:101], 0, v204, s[100:101]
	v_cmp_ge_u32_e64 s[100:101], v7, v135
	v_addc_co_u32_e32 v204, vcc, 0, v204, vcc
	v_cmp_ge_u32_e32 vcc, v14, v135
	v_addc_co_u32_e64 v204, s[98:99], 0, v204, s[98:99]
	v_cmp_ge_u32_e64 s[98:99], v5, v135
	v_addc_co_u32_e64 v204, s[100:101], 0, v204, s[100:101]
	v_cmp_ge_u32_e64 s[100:101], v11, v135
	v_addc_co_u32_e32 v204, vcc, 0, v204, vcc
	v_cmp_ge_u32_e32 vcc, v4, v135
	v_addc_co_u32_e64 v204, s[98:99], 0, v204, s[98:99]
	v_cmp_ge_u32_e64 s[98:99], v22, v135
	v_addc_co_u32_e64 v204, s[100:101], 0, v204, s[100:101]
	v_cmp_ge_u32_e64 s[100:101], v21, v135
	v_addc_co_u32_e32 v204, vcc, 0, v204, vcc
	v_cmp_ge_u32_e32 vcc, v24, v135
	v_addc_co_u32_e64 v204, s[98:99], 0, v204, s[98:99]
	v_cmp_ge_u32_e64 s[98:99], v23, v135
	v_addc_co_u32_e64 v204, s[100:101], 0, v204, s[100:101]
	v_cmp_ge_u32_e64 s[100:101], v26, v135
	v_addc_co_u32_e32 v204, vcc, 0, v204, vcc
	v_cmp_ge_u32_e32 vcc, v25, v135
	v_addc_co_u32_e64 v204, s[98:99], 0, v204, s[98:99]
	v_cmp_ge_u32_e64 s[98:99], v28, v135
	v_addc_co_u32_e64 v204, s[100:101], 0, v204, s[100:101]
	v_cmp_ge_u32_e64 s[100:101], v27, v135
	v_addc_co_u32_e32 v204, vcc, 0, v204, vcc
	v_cmp_ge_u32_e32 vcc, v31, v135
	v_addc_co_u32_e64 v204, s[98:99], 0, v204, s[98:99]
	v_cmp_ge_u32_e64 s[98:99], v29, v135
	v_addc_co_u32_e64 v204, s[100:101], 0, v204, s[100:101]
	v_cmp_ge_u32_e64 s[100:101], v33, v135
	v_addc_co_u32_e32 v204, vcc, 0, v204, vcc
	v_cmp_ge_u32_e32 vcc, v32, v135
	v_addc_co_u32_e64 v204, s[98:99], 0, v204, s[98:99]
	v_cmp_ge_u32_e64 s[98:99], v35, v135
	v_addc_co_u32_e64 v204, s[100:101], 0, v204, s[100:101]
	v_cmp_ge_u32_e64 s[100:101], v34, v135
	v_addc_co_u32_e32 v204, vcc, 0, v204, vcc
	v_cmp_ge_u32_e32 vcc, v37, v135
	v_addc_co_u32_e64 v204, s[98:99], 0, v204, s[98:99]
	v_cmp_ge_u32_e64 s[98:99], v36, v135
	v_addc_co_u32_e64 v204, s[100:101], 0, v204, s[100:101]
	s_nop 1
	v_addc_co_u32_e32 v204, vcc, 0, v204, vcc
	v_addc_co_u32_e64 v204, s[98:99], 0, v204, s[98:99]
	s_nop 0
	s_andn2_b64 vcc, exec, s[6:7]
	s_cbranch_vccnz .LBB0_1346
	v_cmp_ge_u32_e64 s[100:101], v39, v135
	v_cmp_ge_u32_e32 vcc, v38, v135
	v_cmp_ge_u32_e64 s[98:99], v41, v135
	v_addc_co_u32_e64 v204, s[100:101], 0, v204, s[100:101]
	v_cmp_ge_u32_e64 s[100:101], v40, v135
	v_addc_co_u32_e32 v204, vcc, 0, v204, vcc
	v_cmp_ge_u32_e32 vcc, v43, v135
	v_addc_co_u32_e64 v204, s[98:99], 0, v204, s[98:99]
	v_cmp_ge_u32_e64 s[98:99], v42, v135
	v_addc_co_u32_e64 v204, s[100:101], 0, v204, s[100:101]
	v_cmp_ge_u32_e64 s[100:101], v45, v135
	v_addc_co_u32_e32 v204, vcc, 0, v204, vcc
	v_cmp_ge_u32_e32 vcc, v44, v135
	v_addc_co_u32_e64 v204, s[98:99], 0, v204, s[98:99]
	v_cmp_ge_u32_e64 s[98:99], v47, v135
	v_addc_co_u32_e64 v204, s[100:101], 0, v204, s[100:101]
	v_cmp_ge_u32_e64 s[100:101], v46, v135
	v_addc_co_u32_e32 v204, vcc, 0, v204, vcc
	v_cmp_ge_u32_e32 vcc, v49, v135
	v_addc_co_u32_e64 v204, s[98:99], 0, v204, s[98:99]
	v_cmp_ge_u32_e64 s[98:99], v48, v135
	v_addc_co_u32_e64 v204, s[100:101], 0, v204, s[100:101]
	v_cmp_ge_u32_e64 s[100:101], v51, v135
	v_addc_co_u32_e32 v204, vcc, 0, v204, vcc
	v_cmp_ge_u32_e32 vcc, v50, v135
	v_addc_co_u32_e64 v204, s[98:99], 0, v204, s[98:99]
	v_cmp_ge_u32_e64 s[98:99], v53, v135
	v_addc_co_u32_e64 v204, s[100:101], 0, v204, s[100:101]
	v_cmp_ge_u32_e64 s[100:101], v52, v135
	v_addc_co_u32_e32 v204, vcc, 0, v204, vcc
	s_nop 1
	v_addc_co_u32_e64 v204, s[98:99], 0, v204, s[98:99]
	v_addc_co_u32_e64 v204, s[100:101], 0, v204, s[100:101]
	s_nop 0
	s_andn2_b64 vcc, exec, s[8:9]
	s_cbranch_vccz .LBB0_1347

.LBB0_1341:
	v_cmp_ge_u32_e32 vcc, v71, v135
	v_cmp_ge_u32_e64 s[98:99], v70, v135
	v_cmp_ge_u32_e64 s[100:101], v73, v135
	v_addc_co_u32_e32 v204, vcc, 0, v204, vcc
	v_cmp_ge_u32_e32 vcc, v72, v135
	v_addc_co_u32_e64 v204, s[98:99], 0, v204, s[98:99]
	v_cmp_ge_u32_e64 s[98:99], v75, v135
	v_addc_co_u32_e64 v204, s[100:101], 0, v204, s[100:101]
	v_cmp_ge_u32_e64 s[100:101], v74, v135
	v_addc_co_u32_e32 v204, vcc, 0, v204, vcc
	v_cmp_ge_u32_e32 vcc, v77, v135
	v_addc_co_u32_e64 v204, s[98:99], 0, v204, s[98:99]
	v_cmp_ge_u32_e64 s[98:99], v76, v135
	v_addc_co_u32_e64 v204, s[100:101], 0, v204, s[100:101]
	v_cmp_ge_u32_e64 s[100:101], v79, v135
	v_addc_co_u32_e32 v204, vcc, 0, v204, vcc
	v_cmp_ge_u32_e32 vcc, v78, v135
	v_addc_co_u32_e64 v204, s[98:99], 0, v204, s[98:99]
	v_cmp_ge_u32_e64 s[98:99], v81, v135
	v_addc_co_u32_e64 v204, s[100:101], 0, v204, s[100:101]
	v_cmp_ge_u32_e64 s[100:101], v80, v135
	v_addc_co_u32_e32 v204, vcc, 0, v204, vcc
	v_cmp_ge_u32_e32 vcc, v83, v135
	v_addc_co_u32_e64 v204, s[98:99], 0, v204, s[98:99]
	v_cmp_ge_u32_e64 s[98:99], v82, v135
	v_addc_co_u32_e64 v204, s[100:101], 0, v204, s[100:101]
	v_cmp_ge_u32_e64 s[100:101], v85, v135
	v_addc_co_u32_e32 v204, vcc, 0, v204, vcc
	v_cmp_ge_u32_e32 vcc, v84, v135
	v_addc_co_u32_e64 v204, s[98:99], 0, v204, s[98:99]
	s_nop 1
	v_addc_co_u32_e64 v204, s[100:101], 0, v204, s[100:101]
	v_addc_co_u32_e32 v204, vcc, 0, v204, vcc
	s_nop 0
	s_andn2_b64 vcc, exec, s[12:13]
	s_cbranch_vccz .LBB0_1349

.LBB0_1343:
	v_cmp_ge_u32_e64 s[98:99], v103, v135
	v_cmp_ge_u32_e64 s[100:101], v102, v135
	v_cmp_ge_u32_e32 vcc, v105, v135
	v_addc_co_u32_e64 v204, s[98:99], 0, v204, s[98:99]
	v_cmp_ge_u32_e64 s[98:99], v104, v135
	v_addc_co_u32_e64 v204, s[100:101], 0, v204, s[100:101]
	v_cmp_ge_u32_e64 s[100:101], v107, v135
	v_addc_co_u32_e32 v204, vcc, 0, v204, vcc
	v_cmp_ge_u32_e32 vcc, v106, v135
	v_addc_co_u32_e64 v204, s[98:99], 0, v204, s[98:99]
	v_cmp_ge_u32_e64 s[98:99], v109, v135
	v_addc_co_u32_e64 v204, s[100:101], 0, v204, s[100:101]
	v_cmp_ge_u32_e64 s[100:101], v108, v135
	v_addc_co_u32_e32 v204, vcc, 0, v204, vcc
	v_cmp_ge_u32_e32 vcc, v111, v135
	v_addc_co_u32_e64 v204, s[98:99], 0, v204, s[98:99]
	v_cmp_ge_u32_e64 s[98:99], v110, v135
	v_addc_co_u32_e64 v204, s[100:101], 0, v204, s[100:101]
	v_cmp_ge_u32_e64 s[100:101], v113, v135
	v_addc_co_u32_e32 v204, vcc, 0, v204, vcc
	v_cmp_ge_u32_e32 vcc, v112, v135
	v_addc_co_u32_e64 v204, s[98:99], 0, v204, s[98:99]
	v_cmp_ge_u32_e64 s[98:99], v115, v135
	v_addc_co_u32_e64 v204, s[100:101], 0, v204, s[100:101]
	v_cmp_ge_u32_e64 s[100:101], v114, v135
	v_addc_co_u32_e32 v204, vcc, 0, v204, vcc
	v_cmp_ge_u32_e32 vcc, v117, v135
	v_addc_co_u32_e64 v204, s[98:99], 0, v204, s[98:99]
	v_cmp_ge_u32_e64 s[98:99], v116, v135
	v_addc_co_u32_e64 v204, s[100:101], 0, v204, s[100:101]
	s_nop 1
	v_addc_co_u32_e32 v204, vcc, 0, v204, vcc
	v_addc_co_u32_e64 v204, s[98:99], 0, v204, s[98:99]
	s_nop 0
	s_andn2_b64 vcc, exec, s[18:19]
	s_cbranch_vccz .LBB0_1351

.LBB0_1345:
	s_nop 1
	v_add_u32_dpp v205, v204, v204 quad_perm:[1,0,3,2] row_mask:0xf bank_mask:0xf
	s_nop 1
	v_add_u32_dpp v205, v205, v205 quad_perm:[2,3,0,1] row_mask:0xf bank_mask:0xf
	s_nop 1
	v_add_u32_dpp v205, v205, v205 row_half_mirror row_mask:0xf bank_mask:0xf
	s_nop 1
	v_add_u32_dpp v205, v205, v205 row_mirror row_mask:0xf bank_mask:0xf
	s_nop 1
	v_readlane_b32 s98, v205, 0
	v_readlane_b32 s99, v205, 16
	v_readlane_b32 s100, v205, 32
	v_readlane_b32 s101, v205, 48
	s_add_i32 s98, s98, s99
	s_add_i32 s100, s100, s101
	s_add_i32 s31, s98, s100
	s_cmpk_gt_u32 s31, 0xff
	s_mov_b64 s[24:25], 0
	s_cselect_b64 s[22:23], -1, 0
	s_branch .LBB0_1353

.LBB0_1347:
	v_cmp_ge_u32_e64 s[100:101], v55, v135
	v_cmp_ge_u32_e32 vcc, v54, v135
	v_cmp_ge_u32_e64 s[98:99], v57, v135
	v_addc_co_u32_e64 v204, s[100:101], 0, v204, s[100:101]
	v_cmp_ge_u32_e64 s[100:101], v56, v135
	v_addc_co_u32_e32 v204, vcc, 0, v204, vcc
	v_cmp_ge_u32_e32 vcc, v59, v135
	v_addc_co_u32_e64 v204, s[98:99], 0, v204, s[98:99]
	v_cmp_ge_u32_e64 s[98:99], v58, v135
	v_addc_co_u32_e64 v204, s[100:101], 0, v204, s[100:101]
	v_cmp_ge_u32_e64 s[100:101], v61, v135
	v_addc_co_u32_e32 v204, vcc, 0, v204, vcc
	v_cmp_ge_u32_e32 vcc, v60, v135
	v_addc_co_u32_e64 v204, s[98:99], 0, v204, s[98:99]
	v_cmp_ge_u32_e64 s[98:99], v63, v135
	v_addc_co_u32_e64 v204, s[100:101], 0, v204, s[100:101]
	v_cmp_ge_u32_e64 s[100:101], v62, v135
	v_addc_co_u32_e32 v204, vcc, 0, v204, vcc
	v_cmp_ge_u32_e32 vcc, v65, v135
	v_addc_co_u32_e64 v204, s[98:99], 0, v204, s[98:99]
	v_cmp_ge_u32_e64 s[98:99], v64, v135
	v_addc_co_u32_e64 v204, s[100:101], 0, v204, s[100:101]
	v_cmp_ge_u32_e64 s[100:101], v67, v135
	v_addc_co_u32_e32 v204, vcc, 0, v204, vcc
	v_cmp_ge_u32_e32 vcc, v66, v135
	v_addc_co_u32_e64 v204, s[98:99], 0, v204, s[98:99]
	v_cmp_ge_u32_e64 s[98:99], v69, v135
	v_addc_co_u32_e64 v204, s[100:101], 0, v204, s[100:101]
	v_cmp_ge_u32_e64 s[100:101], v68, v135
	v_addc_co_u32_e32 v204, vcc, 0, v204, vcc
	s_nop 1
	v_addc_co_u32_e64 v204, s[98:99], 0, v204, s[98:99]
	v_addc_co_u32_e64 v204, s[100:101], 0, v204, s[100:101]
	s_nop 0
	s_andn2_b64 vcc, exec, s[10:11]
	s_cbranch_vccz .LBB0_1341

.LBB0_1349:
	v_cmp_ge_u32_e32 vcc, v87, v135
	v_cmp_ge_u32_e64 s[98:99], v86, v135
	v_cmp_ge_u32_e64 s[100:101], v89, v135
	v_addc_co_u32_e32 v204, vcc, 0, v204, vcc
	v_cmp_ge_u32_e32 vcc, v88, v135
	v_addc_co_u32_e64 v204, s[98:99], 0, v204, s[98:99]
	v_cmp_ge_u32_e64 s[98:99], v91, v135
	v_addc_co_u32_e64 v204, s[100:101], 0, v204, s[100:101]
	v_cmp_ge_u32_e64 s[100:101], v90, v135
	v_addc_co_u32_e32 v204, vcc, 0, v204, vcc
	v_cmp_ge_u32_e32 vcc, v93, v135
	v_addc_co_u32_e64 v204, s[98:99], 0, v204, s[98:99]
	v_cmp_ge_u32_e64 s[98:99], v92, v135
	v_addc_co_u32_e64 v204, s[100:101], 0, v204, s[100:101]
	v_cmp_ge_u32_e64 s[100:101], v95, v135
	v_addc_co_u32_e32 v204, vcc, 0, v204, vcc
	v_cmp_ge_u32_e32 vcc, v94, v135
	v_addc_co_u32_e64 v204, s[98:99], 0, v204, s[98:99]
	v_cmp_ge_u32_e64 s[98:99], v97, v135
	v_addc_co_u32_e64 v204, s[100:101], 0, v204, s[100:101]
	v_cmp_ge_u32_e64 s[100:101], v96, v135
	v_addc_co_u32_e32 v204, vcc, 0, v204, vcc
	v_cmp_ge_u32_e32 vcc, v99, v135
	v_addc_co_u32_e64 v204, s[98:99], 0, v204, s[98:99]
	v_cmp_ge_u32_e64 s[98:99], v98, v135
	v_addc_co_u32_e64 v204, s[100:101], 0, v204, s[100:101]
	v_cmp_ge_u32_e64 s[100:101], v101, v135
	v_addc_co_u32_e32 v204, vcc, 0, v204, vcc
	v_cmp_ge_u32_e32 vcc, v100, v135
	v_addc_co_u32_e64 v204, s[98:99], 0, v204, s[98:99]
	s_nop 1
	v_addc_co_u32_e64 v204, s[100:101], 0, v204, s[100:101]
	v_addc_co_u32_e32 v204, vcc, 0, v204, vcc
	s_nop 0
	s_andn2_b64 vcc, exec, s[16:17]
	s_cbranch_vccz .LBB0_1343

.LBB0_1351:
	v_cmp_ge_u32_e64 s[98:99], v119, v135
	v_cmp_ge_u32_e64 s[100:101], v118, v135
	v_cmp_ge_u32_e32 vcc, v123, v135
	v_addc_co_u32_e64 v204, s[98:99], 0, v204, s[98:99]
	v_cmp_ge_u32_e64 s[98:99], v120, v135
	v_addc_co_u32_e64 v204, s[100:101], 0, v204, s[100:101]
	v_cmp_ge_u32_e64 s[100:101], v125, v135
	v_addc_co_u32_e32 v204, vcc, 0, v204, vcc
	v_cmp_ge_u32_e32 vcc, v121, v135
	v_addc_co_u32_e64 v204, s[98:99], 0, v204, s[98:99]
	v_cmp_ge_u32_e64 s[98:99], v127, v135
	v_addc_co_u32_e64 v204, s[100:101], 0, v204, s[100:101]
	v_cmp_ge_u32_e64 s[100:101], v122, v135
	v_addc_co_u32_e32 v204, vcc, 0, v204, vcc
	v_cmp_ge_u32_e32 vcc, v129, v135
	v_addc_co_u32_e64 v204, s[98:99], 0, v204, s[98:99]
	v_cmp_ge_u32_e64 s[98:99], v124, v135
	v_addc_co_u32_e64 v204, s[100:101], 0, v204, s[100:101]
	v_cmp_ge_u32_e64 s[100:101], v131, v135
	v_addc_co_u32_e32 v204, vcc, 0, v204, vcc
	v_cmp_ge_u32_e32 vcc, v126, v135
	v_addc_co_u32_e64 v204, s[98:99], 0, v204, s[98:99]
	v_cmp_ge_u32_e64 s[98:99], v132, v135
	v_addc_co_u32_e64 v204, s[100:101], 0, v204, s[100:101]
	v_cmp_ge_u32_e64 s[100:101], v128, v135
	v_addc_co_u32_e32 v204, vcc, 0, v204, vcc
	v_cmp_ge_u32_e32 vcc, v133, v135
	v_addc_co_u32_e64 v204, s[98:99], 0, v204, s[98:99]
	v_cmp_ge_u32_e64 s[98:99], v130, v135
	v_addc_co_u32_e64 v204, s[100:101], 0, v204, s[100:101]
	s_nop 1
	v_addc_co_u32_e32 v204, vcc, 0, v204, vcc
	v_addc_co_u32_e64 v204, s[98:99], 0, v204, s[98:99]
	s_nop 0
	s_and_b64 vcc, exec, s[20:21]
	s_cbranch_vccnz .LBB0_1345
.LBB0_1352:
	s_nop 1
	v_add_u32_dpp v205, v204, v204 quad_perm:[1,0,3,2] row_mask:0xf bank_mask:0xf
	s_nop 1
	v_add_u32_dpp v205, v205, v205 quad_perm:[2,3,0,1] row_mask:0xf bank_mask:0xf
	s_nop 1
	v_add_u32_dpp v205, v205, v205 row_half_mirror row_mask:0xf bank_mask:0xf
	s_nop 1
	v_add_u32_dpp v205, v205, v205 row_mirror row_mask:0xf bank_mask:0xf
	s_nop 1
	v_readlane_b32 s98, v205, 0
	v_readlane_b32 s99, v205, 16
	v_readlane_b32 s100, v205, 32
	v_readlane_b32 s101, v205, 48
	s_add_i32 s98, s98, s99
	s_add_i32 s100, s100, s101
	s_add_i32 s31, s98, s100
	s_mov_b64 s[24:25], -1
	s_mov_b64 s[22:23], 0

.LBB0_3358:
	s_waitcnt vmcnt(0) lgkmcnt(0)
	s_cmpk_lt_u32 s61, 0x400
	s_cbranch_scc1 .LBB0_3365
	v_lshl_or_b32 v3, v6, 23, v172
	s_waitcnt vmcnt(0) lgkmcnt(0)
	v_mov_b32_e32 v204, 0
	v_cmp_ge_u32_e32 vcc, v19, v3
	v_cmp_ge_u32_e64 s[98:99], v13, v3
	v_cmp_ge_u32_e64 s[100:101], v20, v3
	v_addc_co_u32_e32 v204, vcc, 0, v204, vcc
	v_cmp_ge_u32_e32 vcc, v12, v3
	v_addc_co_u32_e64 v204, s[98:99], 0, v204, s[98:99]
	v_cmp_ge_u32_e64 s[98:99], v18, v3
	v_addc_co_u32_e64 v204, s[100:101], 0, v204, s[100:101]
	v_cmp_ge_u32_e64 s[100:101], v10, v3
	v_addc_co_u32_e32 v204, vcc, 0, v204, vcc
	v_cmp_ge_u32_e32 vcc, v17, v3
	v_addc_co_u32_e64 v204, s[98:99], 0, v204, s[98:99]
	v_cmp_ge_u32_e64 s[98:99], v9, v3
	v_addc_co_u32_e64 v204, s[100:101], 0, v204, s[100:101]
	v_cmp_ge_u32_e64 s[100:101], v16, v3
	v_addc_co_u32_e32 v204, vcc, 0, v204, vcc
	v_cmp_ge_u32_e32 vcc, v8, v3
	v_addc_co_u32_e64 v204, s[98:99], 0, v204, s[98:99]
	v_cmp_ge_u32_e64 s[98:99], v15, v3
	v_addc_co_u32_e64 v204, s[100:101], 0, v204, s[100:101]
	v_cmp_ge_u32_e64 s[100:101], v7, v3
	v_addc_co_u32_e32 v204, vcc, 0, v204, vcc
	v_cmp_ge_u32_e32 vcc, v14, v3
	v_addc_co_u32_e64 v204, s[98:99], 0, v204, s[98:99]
	v_cmp_ge_u32_e64 s[98:99], v5, v3
	v_addc_co_u32_e64 v204, s[100:101], 0, v204, s[100:101]
	v_cmp_ge_u32_e64 s[100:101], v11, v3
	v_addc_co_u32_e32 v204, vcc, 0, v204, vcc
	v_cmp_ge_u32_e32 vcc, v4, v3
	v_addc_co_u32_e64 v204, s[98:99], 0, v204, s[98:99]
	v_cmp_ge_u32_e64 s[98:99], v22, v3
	v_addc_co_u32_e64 v204, s[100:101], 0, v204, s[100:101]
	v_cmp_ge_u32_e64 s[100:101], v21, v3
	v_addc_co_u32_e32 v204, vcc, 0, v204, vcc
	v_cmp_ge_u32_e32 vcc, v24, v3
	v_addc_co_u32_e64 v204, s[98:99], 0, v204, s[98:99]
	v_cmp_ge_u32_e64 s[98:99], v23, v3
	v_addc_co_u32_e64 v204, s[100:101], 0, v204, s[100:101]
	v_cmp_ge_u32_e64 s[100:101], v26, v3
	v_addc_co_u32_e32 v204, vcc, 0, v204, vcc
	v_cmp_ge_u32_e32 vcc, v25, v3
	v_addc_co_u32_e64 v204, s[98:99], 0, v204, s[98:99]
	v_cmp_ge_u32_e64 s[98:99], v28, v3
	v_addc_co_u32_e64 v204, s[100:101], 0, v204, s[100:101]
	v_cmp_ge_u32_e64 s[100:101], v27, v3
	v_addc_co_u32_e32 v204, vcc, 0, v204, vcc
	v_cmp_ge_u32_e32 vcc, v31, v3
	v_addc_co_u32_e64 v204, s[98:99], 0, v204, s[98:99]
	v_cmp_ge_u32_e64 s[98:99], v29, v3
	v_addc_co_u32_e64 v204, s[100:101], 0, v204, s[100:101]
	v_cmp_ge_u32_e64 s[100:101], v33, v3
	v_addc_co_u32_e32 v204, vcc, 0, v204, vcc
	v_cmp_ge_u32_e32 vcc, v32, v3
	v_addc_co_u32_e64 v204, s[98:99], 0, v204, s[98:99]
	v_cmp_ge_u32_e64 s[98:99], v35, v3
	v_addc_co_u32_e64 v204, s[100:101], 0, v204, s[100:101]
	v_cmp_ge_u32_e64 s[100:101], v34, v3
	v_addc_co_u32_e32 v204, vcc, 0, v204, vcc
	v_cmp_ge_u32_e32 vcc, v37, v3
	v_addc_co_u32_e64 v204, s[98:99], 0, v204, s[98:99]
	v_cmp_ge_u32_e64 s[98:99], v36, v3
	v_addc_co_u32_e64 v204, s[100:101], 0, v204, s[100:101]
	s_nop 1
	v_addc_co_u32_e32 v204, vcc, 0, v204, vcc
	v_addc_co_u32_e64 v204, s[98:99], 0, v204, s[98:99]
	s_nop 0
	s_cmpk_gt_u32 s61, 0x7ff
	s_cselect_b64 s[0:1], -1, 0
	s_cmpk_lt_u32 s61, 0x800
	s_cbranch_scc1 .LBB0_3590
	v_cmp_ge_u32_e64 s[100:101], v39, v3
	v_cmp_ge_u32_e32 vcc, v38, v3
	v_cmp_ge_u32_e64 s[98:99], v41, v3
	v_addc_co_u32_e64 v204, s[100:101], 0, v204, s[100:101]
	v_cmp_ge_u32_e64 s[100:101], v40, v3
	v_addc_co_u32_e32 v204, vcc, 0, v204, vcc
	v_cmp_ge_u32_e32 vcc, v43, v3
	v_addc_co_u32_e64 v204, s[98:99], 0, v204, s[98:99]
	v_cmp_ge_u32_e64 s[98:99], v42, v3
	v_addc_co_u32_e64 v204, s[100:101], 0, v204, s[100:101]
	v_cmp_ge_u32_e64 s[100:101], v45, v3
	v_addc_co_u32_e32 v204, vcc, 0, v204, vcc
	v_cmp_ge_u32_e32 vcc, v44, v3
	v_addc_co_u32_e64 v204, s[98:99], 0, v204, s[98:99]
	v_cmp_ge_u32_e64 s[98:99], v47, v3
	v_addc_co_u32_e64 v204, s[100:101], 0, v204, s[100:101]
	v_cmp_ge_u32_e64 s[100:101], v46, v3
	v_addc_co_u32_e32 v204, vcc, 0, v204, vcc
	v_cmp_ge_u32_e32 vcc, v49, v3
	v_addc_co_u32_e64 v204, s[98:99], 0, v204, s[98:99]
	v_cmp_ge_u32_e64 s[98:99], v48, v3
	v_addc_co_u32_e64 v204, s[100:101], 0, v204, s[100:101]
	v_cmp_ge_u32_e64 s[100:101], v51, v3
	v_addc_co_u32_e32 v204, vcc, 0, v204, vcc
	v_cmp_ge_u32_e32 vcc, v50, v3
	v_addc_co_u32_e64 v204, s[98:99], 0, v204, s[98:99]
	v_cmp_ge_u32_e64 s[98:99], v53, v3
	v_addc_co_u32_e64 v204, s[100:101], 0, v204, s[100:101]
	v_cmp_ge_u32_e64 s[100:101], v52, v3
	v_addc_co_u32_e32 v204, vcc, 0, v204, vcc
	s_nop 1
	v_addc_co_u32_e64 v204, s[98:99], 0, v204, s[98:99]
	v_addc_co_u32_e64 v204, s[100:101], 0, v204, s[100:101]
	s_nop 0
	s_cmpk_gt_u32 s61, 0xbff
	s_cselect_b64 s[6:7], -1, 0
	s_cmpk_lt_u32 s61, 0xc00
	s_cbranch_scc0 .LBB0_3591

.LBB0_3362:
	v_cmp_ge_u32_e32 vcc, v71, v3
	v_cmp_ge_u32_e64 s[98:99], v70, v3
	v_cmp_ge_u32_e64 s[100:101], v73, v3
	v_addc_co_u32_e32 v204, vcc, 0, v204, vcc
	v_cmp_ge_u32_e32 vcc, v72, v3
	v_addc_co_u32_e64 v204, s[98:99], 0, v204, s[98:99]
	v_cmp_ge_u32_e64 s[98:99], v75, v3
	v_addc_co_u32_e64 v204, s[100:101], 0, v204, s[100:101]
	v_cmp_ge_u32_e64 s[100:101], v74, v3
	v_addc_co_u32_e32 v204, vcc, 0, v204, vcc
	v_cmp_ge_u32_e32 vcc, v77, v3
	v_addc_co_u32_e64 v204, s[98:99], 0, v204, s[98:99]
	v_cmp_ge_u32_e64 s[98:99], v76, v3
	v_addc_co_u32_e64 v204, s[100:101], 0, v204, s[100:101]
	v_cmp_ge_u32_e64 s[100:101], v79, v3
	v_addc_co_u32_e32 v204, vcc, 0, v204, vcc
	v_cmp_ge_u32_e32 vcc, v78, v3
	v_addc_co_u32_e64 v204, s[98:99], 0, v204, s[98:99]
	v_cmp_ge_u32_e64 s[98:99], v81, v3
	v_addc_co_u32_e64 v204, s[100:101], 0, v204, s[100:101]
	v_cmp_ge_u32_e64 s[100:101], v80, v3
	v_addc_co_u32_e32 v204, vcc, 0, v204, vcc
	v_cmp_ge_u32_e32 vcc, v83, v3
	v_addc_co_u32_e64 v204, s[98:99], 0, v204, s[98:99]
	v_cmp_ge_u32_e64 s[98:99], v82, v3
	v_addc_co_u32_e64 v204, s[100:101], 0, v204, s[100:101]
	v_cmp_ge_u32_e64 s[100:101], v85, v3
	v_addc_co_u32_e32 v204, vcc, 0, v204, vcc
	v_cmp_ge_u32_e32 vcc, v84, v3
	v_addc_co_u32_e64 v204, s[98:99], 0, v204, s[98:99]
	s_nop 1
	v_addc_co_u32_e64 v204, s[100:101], 0, v204, s[100:101]
	v_addc_co_u32_e32 v204, vcc, 0, v204, vcc
	s_nop 0
	s_cmpk_gt_u32 s61, 0x13ff
	s_cselect_b64 s[10:11], -1, 0
	s_cmpk_lt_u32 s61, 0x1400
	s_cbranch_scc0 .LBB0_3593

.LBB0_3364:
	v_cmp_ge_u32_e64 s[98:99], v103, v3
	v_cmp_ge_u32_e64 s[100:101], v102, v3
	v_cmp_ge_u32_e32 vcc, v105, v3
	v_addc_co_u32_e64 v204, s[98:99], 0, v204, s[98:99]
	v_cmp_ge_u32_e64 s[98:99], v104, v3
	v_addc_co_u32_e64 v204, s[100:101], 0, v204, s[100:101]
	v_cmp_ge_u32_e64 s[100:101], v107, v3
	v_addc_co_u32_e32 v204, vcc, 0, v204, vcc
	v_cmp_ge_u32_e32 vcc, v106, v3
	v_addc_co_u32_e64 v204, s[98:99], 0, v204, s[98:99]
	v_cmp_ge_u32_e64 s[98:99], v109, v3
	v_addc_co_u32_e64 v204, s[100:101], 0, v204, s[100:101]
	v_cmp_ge_u32_e64 s[100:101], v108, v3
	v_addc_co_u32_e32 v204, vcc, 0, v204, vcc
	v_cmp_ge_u32_e32 vcc, v111, v3
	v_addc_co_u32_e64 v204, s[98:99], 0, v204, s[98:99]
	v_cmp_ge_u32_e64 s[98:99], v110, v3
	v_addc_co_u32_e64 v204, s[100:101], 0, v204, s[100:101]
	v_cmp_ge_u32_e64 s[100:101], v113, v3
	v_addc_co_u32_e32 v204, vcc, 0, v204, vcc
	v_cmp_ge_u32_e32 vcc, v112, v3
	v_addc_co_u32_e64 v204, s[98:99], 0, v204, s[98:99]
	v_cmp_ge_u32_e64 s[98:99], v115, v3
	v_addc_co_u32_e64 v204, s[100:101], 0, v204, s[100:101]
	v_cmp_ge_u32_e64 s[100:101], v114, v3
	v_addc_co_u32_e32 v204, vcc, 0, v204, vcc
	v_cmp_ge_u32_e32 vcc, v117, v3
	v_addc_co_u32_e64 v204, s[98:99], 0, v204, s[98:99]
	v_cmp_ge_u32_e64 s[98:99], v116, v3
	v_addc_co_u32_e64 v204, s[100:101], 0, v204, s[100:101]
	s_nop 1
	v_addc_co_u32_e32 v204, vcc, 0, v204, vcc
	v_addc_co_u32_e64 v204, s[98:99], 0, v204, s[98:99]
	s_nop 0
	s_cmpk_gt_u32 s61, 0x1bff
	s_cselect_b64 s[16:17], -1, 0
	s_cmpk_lt_u32 s61, 0x1c00
	s_cbranch_scc0 .LBB0_3595
	s_branch .LBB0_3596

.LBB0_3368:
	s_cmp_gt_i32 s30, -1
	s_cselect_b64 s[6:7], -1, 0
	s_xor_b64 s[8:9], s[12:13], -1
	s_and_b64 s[6:7], s[8:9], s[6:7]
	s_sub_i32 s4, s22, s5
	s_cmpk_gt_i32 s4, 0x200
	s_cselect_b64 s[8:9], -1, 0
	s_and_b64 s[6:7], s[6:7], s[8:9]
	s_andn2_b64 vcc, exec, s[6:7]
	s_mov_b64 s[6:7], -1
	s_cbranch_vccnz .LBB0_3367
	v_lshl_or_b32 v3, 1, s30, v2
	s_waitcnt vmcnt(0) lgkmcnt(0)
	v_mov_b32_e32 v204, 0
	v_cmp_ge_u32_e32 vcc, v19, v3
	v_cmp_ge_u32_e64 s[98:99], v13, v3
	v_cmp_ge_u32_e64 s[100:101], v20, v3
	v_addc_co_u32_e32 v204, vcc, 0, v204, vcc
	v_cmp_ge_u32_e32 vcc, v12, v3
	v_addc_co_u32_e64 v204, s[98:99], 0, v204, s[98:99]
	v_cmp_ge_u32_e64 s[98:99], v18, v3
	v_addc_co_u32_e64 v204, s[100:101], 0, v204, s[100:101]
	v_cmp_ge_u32_e64 s[100:101], v10, v3
	v_addc_co_u32_e32 v204, vcc, 0, v204, vcc
	v_cmp_ge_u32_e32 vcc, v17, v3
	v_addc_co_u32_e64 v204, s[98:99], 0, v204, s[98:99]
	v_cmp_ge_u32_e64 s[98:99], v9, v3
	v_addc_co_u32_e64 v204, s[100:101], 0, v204, s[100:101]
	v_cmp_ge_u32_e64 s[100:101], v16, v3
	v_addc_co_u32_e32 v204, vcc, 0, v204, vcc
	v_cmp_ge_u32_e32 vcc, v8, v3
	v_addc_co_u32_e64 v204, s[98:99], 0, v204, s[98:99]
	v_cmp_ge_u32_e64 s[98:99], v15, v3
	v_addc_co_u32_e64 v204, s[100:101], 0, v204, s[100:101]
	v_cmp_ge_u32_e64 s[100:101], v7, v3
	v_addc_co_u32_e32 v204, vcc, 0, v204, vcc
	v_cmp_ge_u32_e32 vcc, v14, v3
	v_addc_co_u32_e64 v204, s[98:99], 0, v204, s[98:99]
	v_cmp_ge_u32_e64 s[98:99], v5, v3
	v_addc_co_u32_e64 v204, s[100:101], 0, v204, s[100:101]
	v_cmp_ge_u32_e64 s[100:101], v11, v3
	v_addc_co_u32_e32 v204, vcc, 0, v204, vcc
	v_cmp_ge_u32_e32 vcc, v4, v3
	v_addc_co_u32_e64 v204, s[98:99], 0, v204, s[98:99]
	s_nop 1
	v_addc_co_u32_e64 v204, s[100:101], 0, v204, s[100:101]
	v_addc_co_u32_e32 v204, vcc, 0, v204, vcc
	s_nop 0
	s_andn2_b64 vcc, exec, s[68:69]
	s_cbranch_vccnz .LBB0_3378
	v_cmp_ge_u32_e64 s[98:99], v22, v3
	v_cmp_ge_u32_e64 s[100:101], v21, v3
	v_cmp_ge_u32_e32 vcc, v24, v3
	v_addc_co_u32_e64 v204, s[98:99], 0, v204, s[98:99]
	v_cmp_ge_u32_e64 s[98:99], v23, v3
	v_addc_co_u32_e64 v204, s[100:101], 0, v204, s[100:101]
	v_cmp_ge_u32_e64 s[100:101], v26, v3
	v_addc_co_u32_e32 v204, vcc, 0, v204, vcc
	v_cmp_ge_u32_e32 vcc, v25, v3
	v_addc_co_u32_e64 v204, s[98:99], 0, v204, s[98:99]
	v_cmp_ge_u32_e64 s[98:99], v28, v3
	v_addc_co_u32_e64 v204, s[100:101], 0, v204, s[100:101]
	v_cmp_ge_u32_e64 s[100:101], v27, v3
	v_addc_co_u32_e32 v204, vcc, 0, v204, vcc
	v_cmp_ge_u32_e32 vcc, v31, v3
	v_addc_co_u32_e64 v204, s[98:99], 0, v204, s[98:99]
	v_cmp_ge_u32_e64 s[98:99], v29, v3
	v_addc_co_u32_e64 v204, s[100:101], 0, v204, s[100:101]
	v_cmp_ge_u32_e64 s[100:101], v33, v3
	v_addc_co_u32_e32 v204, vcc, 0, v204, vcc
	v_cmp_ge_u32_e32 vcc, v32, v3
	v_addc_co_u32_e64 v204, s[98:99], 0, v204, s[98:99]
	v_cmp_ge_u32_e64 s[98:99], v35, v3
	v_addc_co_u32_e64 v204, s[100:101], 0, v204, s[100:101]
	v_cmp_ge_u32_e64 s[100:101], v34, v3
	v_addc_co_u32_e32 v204, vcc, 0, v204, vcc
	v_cmp_ge_u32_e32 vcc, v37, v3
	v_addc_co_u32_e64 v204, s[98:99], 0, v204, s[98:99]
	v_cmp_ge_u32_e64 s[98:99], v36, v3
	v_addc_co_u32_e64 v204, s[100:101], 0, v204, s[100:101]
	s_nop 1
	v_addc_co_u32_e32 v204, vcc, 0, v204, vcc
	v_addc_co_u32_e64 v204, s[98:99], 0, v204, s[98:99]
	s_nop 0
	s_andn2_b64 vcc, exec, s[54:55]
	s_cbranch_vccz .LBB0_3379

.LBB0_3372:
	v_cmp_ge_u32_e64 s[100:101], v55, v3
	v_cmp_ge_u32_e32 vcc, v54, v3
	v_cmp_ge_u32_e64 s[98:99], v57, v3
	v_addc_co_u32_e64 v204, s[100:101], 0, v204, s[100:101]
	v_cmp_ge_u32_e64 s[100:101], v56, v3
	v_addc_co_u32_e32 v204, vcc, 0, v204, vcc
	v_cmp_ge_u32_e32 vcc, v59, v3
	v_addc_co_u32_e64 v204, s[98:99], 0, v204, s[98:99]
	v_cmp_ge_u32_e64 s[98:99], v58, v3
	v_addc_co_u32_e64 v204, s[100:101], 0, v204, s[100:101]
	v_cmp_ge_u32_e64 s[100:101], v61, v3
	v_addc_co_u32_e32 v204, vcc, 0, v204, vcc
	v_cmp_ge_u32_e32 vcc, v60, v3
	v_addc_co_u32_e64 v204, s[98:99], 0, v204, s[98:99]
	v_cmp_ge_u32_e64 s[98:99], v63, v3
	v_addc_co_u32_e64 v204, s[100:101], 0, v204, s[100:101]
	v_cmp_ge_u32_e64 s[100:101], v62, v3
	v_addc_co_u32_e32 v204, vcc, 0, v204, vcc
	v_cmp_ge_u32_e32 vcc, v65, v3
	v_addc_co_u32_e64 v204, s[98:99], 0, v204, s[98:99]
	v_cmp_ge_u32_e64 s[98:99], v64, v3
	v_addc_co_u32_e64 v204, s[100:101], 0, v204, s[100:101]
	v_cmp_ge_u32_e64 s[100:101], v67, v3
	v_addc_co_u32_e32 v204, vcc, 0, v204, vcc
	v_cmp_ge_u32_e32 vcc, v66, v3
	v_addc_co_u32_e64 v204, s[98:99], 0, v204, s[98:99]
	v_cmp_ge_u32_e64 s[98:99], v69, v3
	v_addc_co_u32_e64 v204, s[100:101], 0, v204, s[100:101]
	v_cmp_ge_u32_e64 s[100:101], v68, v3
	v_addc_co_u32_e32 v204, vcc, 0, v204, vcc
	s_nop 1
	v_addc_co_u32_e64 v204, s[98:99], 0, v204, s[98:99]
	v_addc_co_u32_e64 v204, s[100:101], 0, v204, s[100:101]
	s_nop 0
	s_andn2_b64 vcc, exec, s[96:97]
	s_cbranch_vccz .LBB0_3381

.LBB0_3374:
	v_cmp_ge_u32_e32 vcc, v87, v3
	v_cmp_ge_u32_e64 s[98:99], v86, v3
	v_cmp_ge_u32_e64 s[100:101], v89, v3
	v_addc_co_u32_e32 v204, vcc, 0, v204, vcc
	v_cmp_ge_u32_e32 vcc, v88, v3
	v_addc_co_u32_e64 v204, s[98:99], 0, v204, s[98:99]
	v_cmp_ge_u32_e64 s[98:99], v91, v3
	v_addc_co_u32_e64 v204, s[100:101], 0, v204, s[100:101]
	v_cmp_ge_u32_e64 s[100:101], v90, v3
	v_addc_co_u32_e32 v204, vcc, 0, v204, vcc
	v_cmp_ge_u32_e32 vcc, v93, v3
	v_addc_co_u32_e64 v204, s[98:99], 0, v204, s[98:99]
	v_cmp_ge_u32_e64 s[98:99], v92, v3
	v_addc_co_u32_e64 v204, s[100:101], 0, v204, s[100:101]
	v_cmp_ge_u32_e64 s[100:101], v95, v3
	v_addc_co_u32_e32 v204, vcc, 0, v204, vcc
	v_cmp_ge_u32_e32 vcc, v94, v3
	v_addc_co_u32_e64 v204, s[98:99], 0, v204, s[98:99]
	v_cmp_ge_u32_e64 s[98:99], v97, v3
	v_addc_co_u32_e64 v204, s[100:101], 0, v204, s[100:101]
	v_cmp_ge_u32_e64 s[100:101], v96, v3
	v_addc_co_u32_e32 v204, vcc, 0, v204, vcc
	v_cmp_ge_u32_e32 vcc, v99, v3
	v_addc_co_u32_e64 v204, s[98:99], 0, v204, s[98:99]
	v_cmp_ge_u32_e64 s[98:99], v98, v3
	v_addc_co_u32_e64 v204, s[100:101], 0, v204, s[100:101]
	v_cmp_ge_u32_e64 s[100:101], v101, v3
	v_addc_co_u32_e32 v204, vcc, 0, v204, vcc
	v_cmp_ge_u32_e32 vcc, v100, v3
	v_addc_co_u32_e64 v204, s[98:99], 0, v204, s[98:99]
	s_nop 1
	v_addc_co_u32_e64 v204, s[100:101], 0, v204, s[100:101]
	v_addc_co_u32_e32 v204, vcc, 0, v204, vcc
	s_nop 0
	s_andn2_b64 vcc, exec, s[66:67]
	s_cbranch_vccz .LBB0_3383

.LBB0_3379:
	v_cmp_ge_u32_e64 s[100:101], v39, v3
	v_cmp_ge_u32_e32 vcc, v38, v3
	v_cmp_ge_u32_e64 s[98:99], v41, v3
	v_addc_co_u32_e64 v204, s[100:101], 0, v204, s[100:101]
	v_cmp_ge_u32_e64 s[100:101], v40, v3
	v_addc_co_u32_e32 v204, vcc, 0, v204, vcc
	v_cmp_ge_u32_e32 vcc, v43, v3
	v_addc_co_u32_e64 v204, s[98:99], 0, v204, s[98:99]
	v_cmp_ge_u32_e64 s[98:99], v42, v3
	v_addc_co_u32_e64 v204, s[100:101], 0, v204, s[100:101]
	v_cmp_ge_u32_e64 s[100:101], v45, v3
	v_addc_co_u32_e32 v204, vcc, 0, v204, vcc
	v_cmp_ge_u32_e32 vcc, v44, v3
	v_addc_co_u32_e64 v204, s[98:99], 0, v204, s[98:99]
	v_cmp_ge_u32_e64 s[98:99], v47, v3
	v_addc_co_u32_e64 v204, s[100:101], 0, v204, s[100:101]
	v_cmp_ge_u32_e64 s[100:101], v46, v3
	v_addc_co_u32_e32 v204, vcc, 0, v204, vcc
	v_cmp_ge_u32_e32 vcc, v49, v3
	v_addc_co_u32_e64 v204, s[98:99], 0, v204, s[98:99]
	v_cmp_ge_u32_e64 s[98:99], v48, v3
	v_addc_co_u32_e64 v204, s[100:101], 0, v204, s[100:101]
	v_cmp_ge_u32_e64 s[100:101], v51, v3
	v_addc_co_u32_e32 v204, vcc, 0, v204, vcc
	v_cmp_ge_u32_e32 vcc, v50, v3
	v_addc_co_u32_e64 v204, s[98:99], 0, v204, s[98:99]
	v_cmp_ge_u32_e64 s[98:99], v53, v3
	v_addc_co_u32_e64 v204, s[100:101], 0, v204, s[100:101]
	v_cmp_ge_u32_e64 s[100:101], v52, v3
	v_addc_co_u32_e32 v204, vcc, 0, v204, vcc
	s_nop 1
	v_addc_co_u32_e64 v204, s[98:99], 0, v204, s[98:99]
	v_addc_co_u32_e64 v204, s[100:101], 0, v204, s[100:101]
	s_nop 0
	s_andn2_b64 vcc, exec, s[0:1]
	s_cbranch_vccz .LBB0_3372

.LBB0_3381:
	v_cmp_ge_u32_e32 vcc, v71, v3
	v_cmp_ge_u32_e64 s[98:99], v70, v3
	v_cmp_ge_u32_e64 s[100:101], v73, v3
	v_addc_co_u32_e32 v204, vcc, 0, v204, vcc
	v_cmp_ge_u32_e32 vcc, v72, v3
	v_addc_co_u32_e64 v204, s[98:99], 0, v204, s[98:99]
	v_cmp_ge_u32_e64 s[98:99], v75, v3
	v_addc_co_u32_e64 v204, s[100:101], 0, v204, s[100:101]
	v_cmp_ge_u32_e64 s[100:101], v74, v3
	v_addc_co_u32_e32 v204, vcc, 0, v204, vcc
	v_cmp_ge_u32_e32 vcc, v77, v3
	v_addc_co_u32_e64 v204, s[98:99], 0, v204, s[98:99]
	v_cmp_ge_u32_e64 s[98:99], v76, v3
	v_addc_co_u32_e64 v204, s[100:101], 0, v204, s[100:101]
	v_cmp_ge_u32_e64 s[100:101], v79, v3
	v_addc_co_u32_e32 v204, vcc, 0, v204, vcc
	v_cmp_ge_u32_e32 vcc, v78, v3
	v_addc_co_u32_e64 v204, s[98:99], 0, v204, s[98:99]
	v_cmp_ge_u32_e64 s[98:99], v81, v3
	v_addc_co_u32_e64 v204, s[100:101], 0, v204, s[100:101]
	v_cmp_ge_u32_e64 s[100:101], v80, v3
	v_addc_co_u32_e32 v204, vcc, 0, v204, vcc
	v_cmp_ge_u32_e32 vcc, v83, v3
	v_addc_co_u32_e64 v204, s[98:99], 0, v204, s[98:99]
	v_cmp_ge_u32_e64 s[98:99], v82, v3
	v_addc_co_u32_e64 v204, s[100:101], 0, v204, s[100:101]
	v_cmp_ge_u32_e64 s[100:101], v85, v3
	v_addc_co_u32_e32 v204, vcc, 0, v204, vcc
	v_cmp_ge_u32_e32 vcc, v84, v3
	v_addc_co_u32_e64 v204, s[98:99], 0, v204, s[98:99]
	s_nop 1
	v_addc_co_u32_e64 v204, s[100:101], 0, v204, s[100:101]
	v_addc_co_u32_e32 v204, vcc, 0, v204, vcc
	s_nop 0
	s_andn2_b64 vcc, exec, s[94:95]
	s_cbranch_vccz .LBB0_3374

.LBB0_3383:
	v_cmp_ge_u32_e64 s[98:99], v103, v3
	v_cmp_ge_u32_e64 s[100:101], v102, v3
	v_cmp_ge_u32_e32 vcc, v105, v3
	v_addc_co_u32_e64 v204, s[98:99], 0, v204, s[98:99]
	v_cmp_ge_u32_e64 s[98:99], v104, v3
	v_addc_co_u32_e64 v204, s[100:101], 0, v204, s[100:101]
	v_cmp_ge_u32_e64 s[100:101], v107, v3
	v_addc_co_u32_e32 v204, vcc, 0, v204, vcc
	v_cmp_ge_u32_e32 vcc, v106, v3
	v_addc_co_u32_e64 v204, s[98:99], 0, v204, s[98:99]
	v_cmp_ge_u32_e64 s[98:99], v109, v3
	v_addc_co_u32_e64 v204, s[100:101], 0, v204, s[100:101]
	v_cmp_ge_u32_e64 s[100:101], v108, v3
	v_addc_co_u32_e32 v204, vcc, 0, v204, vcc
	v_cmp_ge_u32_e32 vcc, v111, v3
	v_addc_co_u32_e64 v204, s[98:99], 0, v204, s[98:99]
	v_cmp_ge_u32_e64 s[98:99], v110, v3
	v_addc_co_u32_e64 v204, s[100:101], 0, v204, s[100:101]
	v_cmp_ge_u32_e64 s[100:101], v113, v3
	v_addc_co_u32_e32 v204, vcc, 0, v204, vcc
	v_cmp_ge_u32_e32 vcc, v112, v3
	v_addc_co_u32_e64 v204, s[98:99], 0, v204, s[98:99]
	v_cmp_ge_u32_e64 s[98:99], v115, v3
	v_addc_co_u32_e64 v204, s[100:101], 0, v204, s[100:101]
	v_cmp_ge_u32_e64 s[100:101], v114, v3
	v_addc_co_u32_e32 v204, vcc, 0, v204, vcc
	v_cmp_ge_u32_e32 vcc, v117, v3
	v_addc_co_u32_e64 v204, s[98:99], 0, v204, s[98:99]
	v_cmp_ge_u32_e64 s[98:99], v116, v3
	v_addc_co_u32_e64 v204, s[100:101], 0, v204, s[100:101]
	s_nop 1
	v_addc_co_u32_e32 v204, vcc, 0, v204, vcc
	v_addc_co_u32_e64 v204, s[98:99], 0, v204, s[98:99]
	s_nop 0
	s_andn2_b64 vcc, exec, s[64:65]
	s_cbranch_vccz .LBB0_3376

.LBB0_3591:
	v_cmp_ge_u32_e64 s[100:101], v55, v3
	v_cmp_ge_u32_e32 vcc, v54, v3
	v_cmp_ge_u32_e64 s[98:99], v57, v3
	v_addc_co_u32_e64 v204, s[100:101], 0, v204, s[100:101]
	v_cmp_ge_u32_e64 s[100:101], v56, v3
	v_addc_co_u32_e32 v204, vcc, 0, v204, vcc
	v_cmp_ge_u32_e32 vcc, v59, v3
	v_addc_co_u32_e64 v204, s[98:99], 0, v204, s[98:99]
	v_cmp_ge_u32_e64 s[98:99], v58, v3
	v_addc_co_u32_e64 v204, s[100:101], 0, v204, s[100:101]
	v_cmp_ge_u32_e64 s[100:101], v61, v3
	v_addc_co_u32_e32 v204, vcc, 0, v204, vcc
	v_cmp_ge_u32_e32 vcc, v60, v3
	v_addc_co_u32_e64 v204, s[98:99], 0, v204, s[98:99]
	v_cmp_ge_u32_e64 s[98:99], v63, v3
	v_addc_co_u32_e64 v204, s[100:101], 0, v204, s[100:101]
	v_cmp_ge_u32_e64 s[100:101], v62, v3
	v_addc_co_u32_e32 v204, vcc, 0, v204, vcc
	v_cmp_ge_u32_e32 vcc, v65, v3
	v_addc_co_u32_e64 v204, s[98:99], 0, v204, s[98:99]
	v_cmp_ge_u32_e64 s[98:99], v64, v3
	v_addc_co_u32_e64 v204, s[100:101], 0, v204, s[100:101]
	v_cmp_ge_u32_e64 s[100:101], v67, v3
	v_addc_co_u32_e32 v204, vcc, 0, v204, vcc
	v_cmp_ge_u32_e32 vcc, v66, v3
	v_addc_co_u32_e64 v204, s[98:99], 0, v204, s[98:99]
	v_cmp_ge_u32_e64 s[98:99], v69, v3
	v_addc_co_u32_e64 v204, s[100:101], 0, v204, s[100:101]
	v_cmp_ge_u32_e64 s[100:101], v68, v3
	v_addc_co_u32_e32 v204, vcc, 0, v204, vcc
	s_nop 1
	v_addc_co_u32_e64 v204, s[98:99], 0, v204, s[98:99]
	v_addc_co_u32_e64 v204, s[100:101], 0, v204, s[100:101]
	s_nop 0
	s_cmpk_gt_u32 s61, 0xfff
	s_cselect_b64 s[8:9], -1, 0
	s_cmpk_lt_u32 s61, 0x1000
	s_cbranch_scc0 .LBB0_3362

.LBB0_3593:
	v_cmp_ge_u32_e32 vcc, v87, v3
	v_cmp_ge_u32_e64 s[98:99], v86, v3
	v_cmp_ge_u32_e64 s[100:101], v89, v3
	v_addc_co_u32_e32 v204, vcc, 0, v204, vcc
	v_cmp_ge_u32_e32 vcc, v88, v3
	v_addc_co_u32_e64 v204, s[98:99], 0, v204, s[98:99]
	v_cmp_ge_u32_e64 s[98:99], v91, v3
	v_addc_co_u32_e64 v204, s[100:101], 0, v204, s[100:101]
	v_cmp_ge_u32_e64 s[100:101], v90, v3
	v_addc_co_u32_e32 v204, vcc, 0, v204, vcc
	v_cmp_ge_u32_e32 vcc, v93, v3
	v_addc_co_u32_e64 v204, s[98:99], 0, v204, s[98:99]
	v_cmp_ge_u32_e64 s[98:99], v92, v3
	v_addc_co_u32_e64 v204, s[100:101], 0, v204, s[100:101]
	v_cmp_ge_u32_e64 s[100:101], v95, v3
	v_addc_co_u32_e32 v204, vcc, 0, v204, vcc
	v_cmp_ge_u32_e32 vcc, v94, v3
	v_addc_co_u32_e64 v204, s[98:99], 0, v204, s[98:99]
	v_cmp_ge_u32_e64 s[98:99], v97, v3
	v_addc_co_u32_e64 v204, s[100:101], 0, v204, s[100:101]
	v_cmp_ge_u32_e64 s[100:101], v96, v3
	v_addc_co_u32_e32 v204, vcc, 0, v204, vcc
	v_cmp_ge_u32_e32 vcc, v99, v3
	v_addc_co_u32_e64 v204, s[98:99], 0, v204, s[98:99]
	v_cmp_ge_u32_e64 s[98:99], v98, v3
	v_addc_co_u32_e64 v204, s[100:101], 0, v204, s[100:101]
	v_cmp_ge_u32_e64 s[100:101], v101, v3
	v_addc_co_u32_e32 v204, vcc, 0, v204, vcc
	v_cmp_ge_u32_e32 vcc, v100, v3
	v_addc_co_u32_e64 v204, s[98:99], 0, v204, s[98:99]
	s_nop 1
	v_addc_co_u32_e64 v204, s[100:101], 0, v204, s[100:101]
	v_addc_co_u32_e32 v204, vcc, 0, v204, vcc
	s_nop 0
	s_cmpk_gt_u32 s61, 0x17ff
	s_cselect_b64 s[14:15], -1, 0
	s_cmpk_lt_u32 s61, 0x1800
	s_cbranch_scc0 .LBB0_3364

.LBB0_3596:
	s_nop 1
	v_add_u32_dpp v205, v204, v204 quad_perm:[1,0,3,2] row_mask:0xf bank_mask:0xf
	s_nop 1
	v_add_u32_dpp v205, v205, v205 quad_perm:[2,3,0,1] row_mask:0xf bank_mask:0xf
	s_nop 1
	v_add_u32_dpp v205, v205, v205 row_half_mirror row_mask:0xf bank_mask:0xf
	s_nop 1
	v_add_u32_dpp v205, v205, v205 row_mirror row_mask:0xf bank_mask:0xf
	s_nop 1
	v_readlane_b32 s98, v205, 0
	v_readlane_b32 s99, v205, 16
	v_readlane_b32 s100, v205, 32
	v_readlane_b32 s101, v205, 48
	s_add_i32 s98, s98, s99
	s_add_i32 s100, s100, s101
	s_add_i32 s4, s98, s100
	s_cmpk_lt_u32 s4, 0x100
	s_cselect_b64 s[18:19], -1, 0
	s_cmpk_gt_u32 s4, 0xff
	s_mov_b32 s5, 0x800000
	s_cselect_b32 s24, s5, 0xff800000
	s_mov_b64 s[12:13], 0
	s_mov_b32 s30, 31
	v_mov_b32_e32 v134, 0
	s_mov_b32 s26, 0
	s_mov_b32 s25, 0
	s_mov_b32 s27, s56
.LBB0_3597:
	v_add_u32_e32 v135, s24, v3
	v_mov_b32_e32 v204, 0
	v_cmp_ge_u32_e32 vcc, v19, v135
	v_cmp_ge_u32_e64 s[98:99], v13, v135
	v_cmp_ge_u32_e64 s[100:101], v20, v135
	v_addc_co_u32_e32 v204, vcc, 0, v204, vcc
	v_cmp_ge_u32_e32 vcc, v12, v135
	v_addc_co_u32_e64 v204, s[98:99], 0, v204, s[98:99]
	v_cmp_ge_u32_e64 s[98:99], v18, v135
	v_addc_co_u32_e64 v204, s[100:101], 0, v204, s[100:101]
	v_cmp_ge_u32_e64 s[100:101], v10, v135
	v_addc_co_u32_e32 v204, vcc, 0, v204, vcc
	v_cmp_ge_u32_e32 vcc, v17, v135
	v_addc_co_u32_e64 v204, s[98:99], 0, v204, s[98:99]
	v_cmp_ge_u32_e64 s[98:99], v9, v135
	v_addc_co_u32_e64 v204, s[100:101], 0, v204, s[100:101]
	v_cmp_ge_u32_e64 s[100:101], v16, v135
	v_addc_co_u32_e32 v204, vcc, 0, v204, vcc
	v_cmp_ge_u32_e32 vcc, v8, v135
	v_addc_co_u32_e64 v204, s[98:99], 0, v204, s[98:99]
	v_cmp_ge_u32_e64 s[98:99], v15, v135
	v_addc_co_u32_e64 v204, s[100:101], 0, v204, s[100:101]
	v_cmp_ge_u32_e64 s[100:101], v7, v135
	v_addc_co_u32_e32 v204, vcc, 0, v204, vcc
	v_cmp_ge_u32_e32 vcc, v14, v135
	v_addc_co_u32_e64 v204, s[98:99], 0, v204, s[98:99]
	v_cmp_ge_u32_e64 s[98:99], v5, v135
	v_addc_co_u32_e64 v204, s[100:101], 0, v204, s[100:101]
	v_cmp_ge_u32_e64 s[100:101], v11, v135
	v_addc_co_u32_e32 v204, vcc, 0, v204, vcc
	v_cmp_ge_u32_e32 vcc, v4, v135
	v_addc_co_u32_e64 v204, s[98:99], 0, v204, s[98:99]
	v_cmp_ge_u32_e64 s[98:99], v22, v135
	v_addc_co_u32_e64 v204, s[100:101], 0, v204, s[100:101]
	v_cmp_ge_u32_e64 s[100:101], v21, v135
	v_addc_co_u32_e32 v204, vcc, 0, v204, vcc
	v_cmp_ge_u32_e32 vcc, v24, v135
	v_addc_co_u32_e64 v204, s[98:99], 0, v204, s[98:99]
	v_cmp_ge_u32_e64 s[98:99], v23, v135
	v_addc_co_u32_e64 v204, s[100:101], 0, v204, s[100:101]
	v_cmp_ge_u32_e64 s[100:101], v26, v135
	v_addc_co_u32_e32 v204, vcc, 0, v204, vcc
	v_cmp_ge_u32_e32 vcc, v25, v135
	v_addc_co_u32_e64 v204, s[98:99], 0, v204, s[98:99]
	v_cmp_ge_u32_e64 s[98:99], v28, v135
	v_addc_co_u32_e64 v204, s[100:101], 0, v204, s[100:101]
	v_cmp_ge_u32_e64 s[100:101], v27, v135
	v_addc_co_u32_e32 v204, vcc, 0, v204, vcc
	v_cmp_ge_u32_e32 vcc, v31, v135
	v_addc_co_u32_e64 v204, s[98:99], 0, v204, s[98:99]
	v_cmp_ge_u32_e64 s[98:99], v29, v135
	v_addc_co_u32_e64 v204, s[100:101], 0, v204, s[100:101]
	v_cmp_ge_u32_e64 s[100:101], v33, v135
	v_addc_co_u32_e32 v204, vcc, 0, v204, vcc
	v_cmp_ge_u32_e32 vcc, v32, v135
	v_addc_co_u32_e64 v204, s[98:99], 0, v204, s[98:99]
	v_cmp_ge_u32_e64 s[98:99], v35, v135
	v_addc_co_u32_e64 v204, s[100:101], 0, v204, s[100:101]
	v_cmp_ge_u32_e64 s[100:101], v34, v135
	v_addc_co_u32_e32 v204, vcc, 0, v204, vcc
	v_cmp_ge_u32_e32 vcc, v37, v135
	v_addc_co_u32_e64 v204, s[98:99], 0, v204, s[98:99]
	v_cmp_ge_u32_e64 s[98:99], v36, v135
	v_addc_co_u32_e64 v204, s[100:101], 0, v204, s[100:101]
	s_nop 1
	v_addc_co_u32_e32 v204, vcc, 0, v204, vcc
	v_addc_co_u32_e64 v204, s[98:99], 0, v204, s[98:99]
	s_nop 0
	s_andn2_b64 vcc, exec, s[0:1]
	s_cbranch_vccnz .LBB0_3605
	v_cmp_ge_u32_e64 s[100:101], v39, v135
	v_cmp_ge_u32_e32 vcc, v38, v135
	v_cmp_ge_u32_e64 s[98:99], v41, v135
	v_addc_co_u32_e64 v204, s[100:101], 0, v204, s[100:101]
	v_cmp_ge_u32_e64 s[100:101], v40, v135
	v_addc_co_u32_e32 v204, vcc, 0, v204, vcc
	v_cmp_ge_u32_e32 vcc, v43, v135
	v_addc_co_u32_e64 v204, s[98:99], 0, v204, s[98:99]
	v_cmp_ge_u32_e64 s[98:99], v42, v135
	v_addc_co_u32_e64 v204, s[100:101], 0, v204, s[100:101]
	v_cmp_ge_u32_e64 s[100:101], v45, v135
	v_addc_co_u32_e32 v204, vcc, 0, v204, vcc
	v_cmp_ge_u32_e32 vcc, v44, v135
	v_addc_co_u32_e64 v204, s[98:99], 0, v204, s[98:99]
	v_cmp_ge_u32_e64 s[98:99], v47, v135
	v_addc_co_u32_e64 v204, s[100:101], 0, v204, s[100:101]
	v_cmp_ge_u32_e64 s[100:101], v46, v135
	v_addc_co_u32_e32 v204, vcc, 0, v204, vcc
	v_cmp_ge_u32_e32 vcc, v49, v135
	v_addc_co_u32_e64 v204, s[98:99], 0, v204, s[98:99]
	v_cmp_ge_u32_e64 s[98:99], v48, v135
	v_addc_co_u32_e64 v204, s[100:101], 0, v204, s[100:101]
	v_cmp_ge_u32_e64 s[100:101], v51, v135
	v_addc_co_u32_e32 v204, vcc, 0, v204, vcc
	v_cmp_ge_u32_e32 vcc, v50, v135
	v_addc_co_u32_e64 v204, s[98:99], 0, v204, s[98:99]
	v_cmp_ge_u32_e64 s[98:99], v53, v135
	v_addc_co_u32_e64 v204, s[100:101], 0, v204, s[100:101]
	v_cmp_ge_u32_e64 s[100:101], v52, v135
	v_addc_co_u32_e32 v204, vcc, 0, v204, vcc
	s_nop 1
	v_addc_co_u32_e64 v204, s[98:99], 0, v204, s[98:99]
	v_addc_co_u32_e64 v204, s[100:101], 0, v204, s[100:101]
	s_nop 0
	s_andn2_b64 vcc, exec, s[6:7]
	s_cbranch_vccz .LBB0_3606

.LBB0_3600:
	v_cmp_ge_u32_e32 vcc, v71, v135
	v_cmp_ge_u32_e64 s[98:99], v70, v135
	v_cmp_ge_u32_e64 s[100:101], v73, v135
	v_addc_co_u32_e32 v204, vcc, 0, v204, vcc
	v_cmp_ge_u32_e32 vcc, v72, v135
	v_addc_co_u32_e64 v204, s[98:99], 0, v204, s[98:99]
	v_cmp_ge_u32_e64 s[98:99], v75, v135
	v_addc_co_u32_e64 v204, s[100:101], 0, v204, s[100:101]
	v_cmp_ge_u32_e64 s[100:101], v74, v135
	v_addc_co_u32_e32 v204, vcc, 0, v204, vcc
	v_cmp_ge_u32_e32 vcc, v77, v135
	v_addc_co_u32_e64 v204, s[98:99], 0, v204, s[98:99]
	v_cmp_ge_u32_e64 s[98:99], v76, v135
	v_addc_co_u32_e64 v204, s[100:101], 0, v204, s[100:101]
	v_cmp_ge_u32_e64 s[100:101], v79, v135
	v_addc_co_u32_e32 v204, vcc, 0, v204, vcc
	v_cmp_ge_u32_e32 vcc, v78, v135
	v_addc_co_u32_e64 v204, s[98:99], 0, v204, s[98:99]
	v_cmp_ge_u32_e64 s[98:99], v81, v135
	v_addc_co_u32_e64 v204, s[100:101], 0, v204, s[100:101]
	v_cmp_ge_u32_e64 s[100:101], v80, v135
	v_addc_co_u32_e32 v204, vcc, 0, v204, vcc
	v_cmp_ge_u32_e32 vcc, v83, v135
	v_addc_co_u32_e64 v204, s[98:99], 0, v204, s[98:99]
	v_cmp_ge_u32_e64 s[98:99], v82, v135
	v_addc_co_u32_e64 v204, s[100:101], 0, v204, s[100:101]
	v_cmp_ge_u32_e64 s[100:101], v85, v135
	v_addc_co_u32_e32 v204, vcc, 0, v204, vcc
	v_cmp_ge_u32_e32 vcc, v84, v135
	v_addc_co_u32_e64 v204, s[98:99], 0, v204, s[98:99]
	s_nop 1
	v_addc_co_u32_e64 v204, s[100:101], 0, v204, s[100:101]
	v_addc_co_u32_e32 v204, vcc, 0, v204, vcc
	s_nop 0
	s_andn2_b64 vcc, exec, s[10:11]
	s_cbranch_vccz .LBB0_3608

.LBB0_3602:
	v_cmp_ge_u32_e64 s[98:99], v103, v135
	v_cmp_ge_u32_e64 s[100:101], v102, v135
	v_cmp_ge_u32_e32 vcc, v105, v135
	v_addc_co_u32_e64 v204, s[98:99], 0, v204, s[98:99]
	v_cmp_ge_u32_e64 s[98:99], v104, v135
	v_addc_co_u32_e64 v204, s[100:101], 0, v204, s[100:101]
	v_cmp_ge_u32_e64 s[100:101], v107, v135
	v_addc_co_u32_e32 v204, vcc, 0, v204, vcc
	v_cmp_ge_u32_e32 vcc, v106, v135
	v_addc_co_u32_e64 v204, s[98:99], 0, v204, s[98:99]
	v_cmp_ge_u32_e64 s[98:99], v109, v135
	v_addc_co_u32_e64 v204, s[100:101], 0, v204, s[100:101]
	v_cmp_ge_u32_e64 s[100:101], v108, v135
	v_addc_co_u32_e32 v204, vcc, 0, v204, vcc
	v_cmp_ge_u32_e32 vcc, v111, v135
	v_addc_co_u32_e64 v204, s[98:99], 0, v204, s[98:99]
	v_cmp_ge_u32_e64 s[98:99], v110, v135
	v_addc_co_u32_e64 v204, s[100:101], 0, v204, s[100:101]
	v_cmp_ge_u32_e64 s[100:101], v113, v135
	v_addc_co_u32_e32 v204, vcc, 0, v204, vcc
	v_cmp_ge_u32_e32 vcc, v112, v135
	v_addc_co_u32_e64 v204, s[98:99], 0, v204, s[98:99]
	v_cmp_ge_u32_e64 s[98:99], v115, v135
	v_addc_co_u32_e64 v204, s[100:101], 0, v204, s[100:101]
	v_cmp_ge_u32_e64 s[100:101], v114, v135
	v_addc_co_u32_e32 v204, vcc, 0, v204, vcc
	v_cmp_ge_u32_e32 vcc, v117, v135
	v_addc_co_u32_e64 v204, s[98:99], 0, v204, s[98:99]
	v_cmp_ge_u32_e64 s[98:99], v116, v135
	v_addc_co_u32_e64 v204, s[100:101], 0, v204, s[100:101]
	s_nop 1
	v_addc_co_u32_e32 v204, vcc, 0, v204, vcc
	v_addc_co_u32_e64 v204, s[98:99], 0, v204, s[98:99]
	s_nop 0
	s_andn2_b64 vcc, exec, s[16:17]
	s_cbranch_vccz .LBB0_3610

.LBB0_3604:
	s_nop 1
	v_add_u32_dpp v205, v204, v204 quad_perm:[1,0,3,2] row_mask:0xf bank_mask:0xf
	s_nop 1
	v_add_u32_dpp v205, v205, v205 quad_perm:[2,3,0,1] row_mask:0xf bank_mask:0xf
	s_nop 1
	v_add_u32_dpp v205, v205, v205 row_half_mirror row_mask:0xf bank_mask:0xf
	s_nop 1
	v_add_u32_dpp v205, v205, v205 row_mirror row_mask:0xf bank_mask:0xf
	s_nop 1
	v_readlane_b32 s98, v205, 0
	v_readlane_b32 s99, v205, 16
	v_readlane_b32 s100, v205, 32
	v_readlane_b32 s101, v205, 48
	s_add_i32 s98, s98, s99
	s_add_i32 s100, s100, s101
	s_add_i32 s28, s98, s100
	s_cmpk_gt_u32 s28, 0xff
	s_mov_b64 s[22:23], 0
	s_cselect_b64 s[20:21], -1, 0
	s_branch .LBB0_3612

.LBB0_3606:
	v_cmp_ge_u32_e64 s[100:101], v55, v135
	v_cmp_ge_u32_e32 vcc, v54, v135
	v_cmp_ge_u32_e64 s[98:99], v57, v135
	v_addc_co_u32_e64 v204, s[100:101], 0, v204, s[100:101]
	v_cmp_ge_u32_e64 s[100:101], v56, v135
	v_addc_co_u32_e32 v204, vcc, 0, v204, vcc
	v_cmp_ge_u32_e32 vcc, v59, v135
	v_addc_co_u32_e64 v204, s[98:99], 0, v204, s[98:99]
	v_cmp_ge_u32_e64 s[98:99], v58, v135
	v_addc_co_u32_e64 v204, s[100:101], 0, v204, s[100:101]
	v_cmp_ge_u32_e64 s[100:101], v61, v135
	v_addc_co_u32_e32 v204, vcc, 0, v204, vcc
	v_cmp_ge_u32_e32 vcc, v60, v135
	v_addc_co_u32_e64 v204, s[98:99], 0, v204, s[98:99]
	v_cmp_ge_u32_e64 s[98:99], v63, v135
	v_addc_co_u32_e64 v204, s[100:101], 0, v204, s[100:101]
	v_cmp_ge_u32_e64 s[100:101], v62, v135
	v_addc_co_u32_e32 v204, vcc, 0, v204, vcc
	v_cmp_ge_u32_e32 vcc, v65, v135
	v_addc_co_u32_e64 v204, s[98:99], 0, v204, s[98:99]
	v_cmp_ge_u32_e64 s[98:99], v64, v135
	v_addc_co_u32_e64 v204, s[100:101], 0, v204, s[100:101]
	v_cmp_ge_u32_e64 s[100:101], v67, v135
	v_addc_co_u32_e32 v204, vcc, 0, v204, vcc
	v_cmp_ge_u32_e32 vcc, v66, v135
	v_addc_co_u32_e64 v204, s[98:99], 0, v204, s[98:99]
	v_cmp_ge_u32_e64 s[98:99], v69, v135
	v_addc_co_u32_e64 v204, s[100:101], 0, v204, s[100:101]
	v_cmp_ge_u32_e64 s[100:101], v68, v135
	v_addc_co_u32_e32 v204, vcc, 0, v204, vcc
	s_nop 1
	v_addc_co_u32_e64 v204, s[98:99], 0, v204, s[98:99]
	v_addc_co_u32_e64 v204, s[100:101], 0, v204, s[100:101]
	s_nop 0
	s_andn2_b64 vcc, exec, s[8:9]
	s_cbranch_vccz .LBB0_3600

.LBB0_3608:
	v_cmp_ge_u32_e32 vcc, v87, v135
	v_cmp_ge_u32_e64 s[98:99], v86, v135
	v_cmp_ge_u32_e64 s[100:101], v89, v135
	v_addc_co_u32_e32 v204, vcc, 0, v204, vcc
	v_cmp_ge_u32_e32 vcc, v88, v135
	v_addc_co_u32_e64 v204, s[98:99], 0, v204, s[98:99]
	v_cmp_ge_u32_e64 s[98:99], v91, v135
	v_addc_co_u32_e64 v204, s[100:101], 0, v204, s[100:101]
	v_cmp_ge_u32_e64 s[100:101], v90, v135
	v_addc_co_u32_e32 v204, vcc, 0, v204, vcc
	v_cmp_ge_u32_e32 vcc, v93, v135
	v_addc_co_u32_e64 v204, s[98:99], 0, v204, s[98:99]
	v_cmp_ge_u32_e64 s[98:99], v92, v135
	v_addc_co_u32_e64 v204, s[100:101], 0, v204, s[100:101]
	v_cmp_ge_u32_e64 s[100:101], v95, v135
	v_addc_co_u32_e32 v204, vcc, 0, v204, vcc
	v_cmp_ge_u32_e32 vcc, v94, v135
	v_addc_co_u32_e64 v204, s[98:99], 0, v204, s[98:99]
	v_cmp_ge_u32_e64 s[98:99], v97, v135
	v_addc_co_u32_e64 v204, s[100:101], 0, v204, s[100:101]
	v_cmp_ge_u32_e64 s[100:101], v96, v135
	v_addc_co_u32_e32 v204, vcc, 0, v204, vcc
	v_cmp_ge_u32_e32 vcc, v99, v135
	v_addc_co_u32_e64 v204, s[98:99], 0, v204, s[98:99]
	v_cmp_ge_u32_e64 s[98:99], v98, v135
	v_addc_co_u32_e64 v204, s[100:101], 0, v204, s[100:101]
	v_cmp_ge_u32_e64 s[100:101], v101, v135
	v_addc_co_u32_e32 v204, vcc, 0, v204, vcc
	v_cmp_ge_u32_e32 vcc, v100, v135
	v_addc_co_u32_e64 v204, s[98:99], 0, v204, s[98:99]
	s_nop 1
	v_addc_co_u32_e64 v204, s[100:101], 0, v204, s[100:101]
	v_addc_co_u32_e32 v204, vcc, 0, v204, vcc
	s_nop 0
	s_andn2_b64 vcc, exec, s[14:15]
	s_cbranch_vccz .LBB0_3602

.LBB0_3610:
	v_cmp_ge_u32_e64 s[98:99], v119, v135
	v_cmp_ge_u32_e64 s[100:101], v118, v135
	v_cmp_ge_u32_e32 vcc, v123, v135
	v_addc_co_u32_e64 v204, s[98:99], 0, v204, s[98:99]
	v_cmp_ge_u32_e64 s[98:99], v120, v135
	v_addc_co_u32_e64 v204, s[100:101], 0, v204, s[100:101]
	v_cmp_ge_u32_e64 s[100:101], v125, v135
	v_addc_co_u32_e32 v204, vcc, 0, v204, vcc
	v_cmp_ge_u32_e32 vcc, v121, v135
	v_addc_co_u32_e64 v204, s[98:99], 0, v204, s[98:99]
	v_cmp_ge_u32_e64 s[98:99], v127, v135
	v_addc_co_u32_e64 v204, s[100:101], 0, v204, s[100:101]
	v_cmp_ge_u32_e64 s[100:101], v122, v135
	v_addc_co_u32_e32 v204, vcc, 0, v204, vcc
	v_cmp_ge_u32_e32 vcc, v129, v135
	v_addc_co_u32_e64 v204, s[98:99], 0, v204, s[98:99]
	v_cmp_ge_u32_e64 s[98:99], v124, v135
	v_addc_co_u32_e64 v204, s[100:101], 0, v204, s[100:101]
	v_cmp_ge_u32_e64 s[100:101], v131, v135
	v_addc_co_u32_e32 v204, vcc, 0, v204, vcc
	v_cmp_ge_u32_e32 vcc, v126, v135
	v_addc_co_u32_e64 v204, s[98:99], 0, v204, s[98:99]
	v_cmp_ge_u32_e64 s[98:99], v132, v135
	v_addc_co_u32_e64 v204, s[100:101], 0, v204, s[100:101]
	v_cmp_ge_u32_e64 s[100:101], v128, v135
	v_addc_co_u32_e32 v204, vcc, 0, v204, vcc
	v_cmp_ge_u32_e32 vcc, v133, v135
	v_addc_co_u32_e64 v204, s[98:99], 0, v204, s[98:99]
	v_cmp_ge_u32_e64 s[98:99], v130, v135
	v_addc_co_u32_e64 v204, s[100:101], 0, v204, s[100:101]
	s_nop 1
	v_addc_co_u32_e32 v204, vcc, 0, v204, vcc
	v_addc_co_u32_e64 v204, s[98:99], 0, v204, s[98:99]
	s_nop 0
	s_and_b64 vcc, exec, s[18:19]
	s_cbranch_vccnz .LBB0_3604
.LBB0_3611:
	s_nop 1
	v_add_u32_dpp v205, v204, v204 quad_perm:[1,0,3,2] row_mask:0xf bank_mask:0xf
	s_nop 1
	v_add_u32_dpp v205, v205, v205 quad_perm:[2,3,0,1] row_mask:0xf bank_mask:0xf
	s_nop 1
	v_add_u32_dpp v205, v205, v205 row_half_mirror row_mask:0xf bank_mask:0xf
	s_nop 1
	v_add_u32_dpp v205, v205, v205 row_mirror row_mask:0xf bank_mask:0xf
	s_nop 1
	v_readlane_b32 s98, v205, 0
	v_readlane_b32 s99, v205, 16
	v_readlane_b32 s100, v205, 32
	v_readlane_b32 s101, v205, 48
	s_add_i32 s98, s98, s99
	s_add_i32 s100, s100, s101
	s_add_i32 s28, s98, s100
	s_mov_b64 s[22:23], -1
	s_mov_b64 s[20:21], 0
